# same code, 64 bytes of padding in a never-taken fallback path (code placement of the following GEMM loops)
# speedup vs baseline: 1.0111x; 1.0003x over previous
; #define MFMA(a, b, c) __builtin_amdgcn_mfma_f32_32x32x16_bf16((a), (b), (c), 0, 0, 0)
; template <int TM, int TN>
; DI void gemm_mainloop(const u16* __restrict__ A, long lda, const u16* __restrict__ Bt, long ldb, int K, char* smem,
;                       f32x16 (&acc)[TM][TN]) {
;     ...
;   const int nk = K / 64;
;   const int lrow = tid >> 3, lch = (tid & 7) * 8;
;   const u16* gA = A + (long)lrow * lda + lch;
;   const u16* gB = Bt + (long)lrow * ldb + lch;
;   const int soff = lrow * LD + lch;
;     ...
;   GEMM_GLOAD(0)
;   __syncthreads();
;   GEMM_SSTORE(0)
;   if (nk > 1) GEMM_GLOAD(64)
;   __syncthreads();
;   for (int kt = 0; kt < nk; kt++) {
;     const int buf = kt & 1;
;     const u16* cA = sA + buf * BM * LD + (wm * 32 * TM + r) * LD + h * 8;
;     const u16* cB = sB + buf * BN * LD + (wn * 32 * TN + r) * LD + h * 8;
;     bf16x8 af[TM], bfr[TN];
; #pragma unroll
;     for (int tm = 0; tm < TM; tm++) af[tm] = *(const bf16x8*)(cA + tm * 32 * LD);
; #pragma unroll
;     for (int tn = 0; tn < TN; tn++) bfr[tn] = *(const bf16x8*)(cB + tn * 32 * LD);
;     if (kt + 1 < nk) GEMM_SSTORE(buf ^ 1)
;     __builtin_amdgcn_sched_barrier(0);
;     __builtin_amdgcn_s_setprio(1);
; #pragma unroll
;     for (int tm = 0; tm < TM; tm++)
; #pragma unroll
;       for (int tn = 0; tn < TN; tn++) acc[tm][tn] = MFMA(af[tm], bfr[tn], acc[tm][tn]);
; #pragma unroll
;     for (int tm = 0; tm < TM; tm++) af[tm] = *(const bf16x8*)(cA + tm * 32 * LD + 16);
; #pragma unroll
;     for (int tn = 0; tn < TN; tn++) bfr[tn] = *(const bf16x8*)(cB + tn * 32 * LD + 16);
; #pragma unroll
;     for (int tm = 0; tm < TM; tm++)
; #pragma unroll
;       for (int tn = 0; tn < TN; tn++) acc[tm][tn] = MFMA(af[tm], bfr[tn], acc[tm][tn]);
;     __builtin_amdgcn_sched_group_barrier(0x8, 4, 0);
;     if (kt + 2 < nk) GEMM_GLOAD((kt + 2) * 64)
; #pragma unroll
;     for (int ks = 2; ks < 4; ks++) {
; #pragma unroll
;       for (int tm = 0; tm < TM; tm++) af[tm] = *(const bf16x8*)(cA + tm * 32 * LD + ks * 16);
; #pragma unroll
;       for (int tn = 0; tn < TN; tn++) bfr[tn] = *(const bf16x8*)(cB + tn * 32 * LD + ks * 16);
; #pragma unroll
;       for (int tm = 0; tm < TM; tm++)
; #pragma unroll
;         for (int tn = 0; tn < TN; tn++) acc[tm][tn] = MFMA(af[tm], bfr[tn], acc[tm][tn]);
;     }
.LBB0_2739:
	s_nop 0
	s_nop 0
	s_nop 0
	s_nop 0
	s_nop 0
	s_nop 0
	s_nop 0
	s_nop 0
	s_nop 0
	s_nop 0
	s_nop 0
	s_nop 0
	s_nop 0
	s_nop 0
	s_nop 0
	s_nop 0
	s_ashr_i32 s6, s22, 31
	s_lshr_b32 s6, s6, 27
	s_add_i32 s6, s22, s6
	s_and_b32 s7, s6, 0xffffffe0
	s_lshl_b32 s6, s6, 2
	s_sub_i32 s26, s22, s7
	s_and_b32 s23, s6, 0xffffff80
	s_lshl_b32 s6, s26, 7
	s_mul_i32 s24, s23, 0x880
	s_mul_hi_i32 s7, s23, 0x880
	s_add_u32 s24, s4, s24
	v_mov_b32_e32 v1, v0
	s_addc_u32 s25, s5, s7
	s_ashr_i32 s7, s6, 31
	v_lshlrev_b32_e32 v2, 3, v1
	v_ashrrev_i32_e32 v68, 3, v1
	v_and_b32_e32 v69, 56, v2
	v_mov_b64_e32 v[2:3], s[24:25]
	v_mad_i64_i32 v[2:3], s[24:25], v68, s8, v[2:3]
	v_lshlrev_b32_e32 v66, 1, v69
	v_lshl_add_u64 v[72:73], v[2:3], 0, v[66:67]
	s_mul_i32 s26, s26, 0x44000
	v_add_co_u32_e32 v70, vcc, s15, v72
	s_mul_hi_i32 s27, s6, 0x880
	s_add_u32 s26, s11, s26
	v_addc_co_u32_e32 v71, vcc, 0, v73, vcc
	s_addc_u32 s27, s14, s27
	v_add_co_u32_e32 v74, vcc, s16, v72
	v_mov_b64_e32 v[2:3], s[26:27]
	s_nop 0
	v_addc_co_u32_e32 v75, vcc, 0, v73, vcc
	v_mad_i64_i32 v[18:19], s[24:25], v68, s8, v[2:3]
	v_add_co_u32_e32 v78, vcc, s17, v72
	v_lshl_add_u64 v[76:77], v[18:19], 0, v[66:67]
	s_nop 0
	v_addc_co_u32_e32 v79, vcc, 0, v73, vcc
	v_add_co_u32_e32 v80, vcc, s15, v76
	global_load_dwordx4 v[2:5], v[72:73], off
	s_nop 0
	v_addc_co_u32_e32 v81, vcc, 0, v77, vcc
	v_add_co_u32_e32 v82, vcc, s16, v76
	global_load_dwordx4 v[6:9], v[70:71], off
	s_nop 0
	v_addc_co_u32_e32 v83, vcc, 0, v77, vcc
	v_add_co_u32_e32 v84, vcc, s17, v76
	global_load_dwordx4 v[10:13], v[74:75], off
	s_nop 0
	v_addc_co_u32_e32 v85, vcc, 0, v77, vcc
	global_load_dwordx4 v[14:17], v[78:79], off
	global_load_dwordx4 v[18:21], v[76:77], off
	global_load_dwordx4 v[22:25], v[80:81], off
	global_load_dwordx4 v[26:29], v[82:83], off
	global_load_dwordx4 v[30:33], v[84:85], off
	s_barrier
	global_load_dwordx4 v[34:37], v[72:73], off offset:128
	global_load_dwordx4 v[38:41], v[70:71], off offset:128
	global_load_dwordx4 v[42:45], v[74:75], off offset:128
	global_load_dwordx4 v[46:49], v[78:79], off offset:128
	global_load_dwordx4 v[50:53], v[76:77], off offset:128
	global_load_dwordx4 v[54:57], v[80:81], off offset:128
	global_load_dwordx4 v[58:61], v[82:83], off offset:128
	global_load_dwordx4 v[62:65], v[84:85], off offset:128
	v_and_b32_e32 v66, 31, v1
	v_lshrrev_b32_e32 v86, 1, v1
	v_mul_lo_u32 v68, v68, s9
	v_and_or_b32 v87, v86, s18, v66
	v_and_b32_e32 v86, 16, v86
	v_and_b32_e32 v1, 0x5f, v1
	v_add_lshl_u32 v66, v68, v69, 1
	v_mad_u64_u32 v[68:69], s[24:25], v87, s19, v[86:87]
	v_mad_u32_u24 v1, v1, s19, v86
	v_add_u32_e32 v69, 0x9000, v66
	s_waitcnt vmcnt(15)
	ds_write_b128 v66, v[2:5]
	s_waitcnt vmcnt(14)
	ds_write_b128 v66, v[6:9] offset:4608
	s_waitcnt vmcnt(13)
	ds_write_b128 v66, v[10:13] offset:9216
	s_waitcnt vmcnt(12)
	ds_write_b128 v66, v[14:17] offset:13824
	s_waitcnt vmcnt(11)
	ds_write_b128 v66, v[18:21] offset:36864
	s_waitcnt vmcnt(10)
	ds_write_b128 v66, v[22:25] offset:41472
	s_waitcnt vmcnt(9)
	ds_write_b128 v66, v[26:29] offset:46080
	s_waitcnt vmcnt(8)
	ds_write_b128 v66, v[30:33] offset:50688
	s_waitcnt lgkmcnt(0)
	s_barrier
	ds_read_b128 v[2:5], v68
	ds_read_b128 v[18:21], v68 offset:4608
	ds_read_b128 v[6:9], v1 offset:36864
	ds_read_b128 v[22:25], v1 offset:41472
	s_waitcnt vmcnt(7)
	ds_write_b128 v66, v[34:37] offset:18432
	s_waitcnt vmcnt(6)
	ds_write_b128 v66, v[38:41] offset:23040
	s_waitcnt vmcnt(5)
	ds_write_b128 v66, v[42:45] offset:27648
	s_waitcnt vmcnt(4)
	ds_write_b128 v66, v[46:49] offset:32256
	s_waitcnt vmcnt(3)
	ds_write_b128 v66, v[50:53] offset:55296
	s_waitcnt vmcnt(2)
	ds_write_b128 v66, v[54:57] offset:59904
	s_waitcnt vmcnt(1)
	ds_write_b128 v66, v[58:61] offset:64512
	s_waitcnt vmcnt(0)
	ds_write_b128 v69, v[62:65] offset:32256
	s_setprio 1
	ds_read_b128 v[86:89], v68 offset:32
	s_waitcnt lgkmcnt(10)
	v_mfma_f32_32x32x16_bf16 v[34:49], v[2:5], v[6:9], 0
	ds_read_b128 v[90:93], v1 offset:36896
	ds_read_b128 v[94:97], v1 offset:41504
	ds_read_b128 v[98:101], v68 offset:4704
	global_load_dwordx4 v[102:105], v[70:71], off offset:256
	global_load_dwordx4 v[106:109], v[74:75], off offset:256
	global_load_dwordx4 v[110:113], v[78:79], off offset:256
	global_load_dwordx4 v[114:117], v[84:85], off offset:256
	s_waitcnt lgkmcnt(12)
	v_mfma_f32_32x32x16_bf16 v[50:65], v[2:5], v[22:25], 0
	global_load_dwordx4 v[118:121], v[82:83], off offset:256
	global_load_dwordx4 v[122:125], v[80:81], off offset:256
	global_load_dwordx4 v[140:143], v[72:73], off offset:256
	global_load_dwordx4 v[144:147], v[76:77], off offset:256
	s_waitcnt lgkmcnt(2)
	v_mfma_f32_32x32x16_bf16 v[34:49], v[86:89], v[90:93], v[34:49]
	s_waitcnt lgkmcnt(1)
	v_mfma_f32_32x32x16_bf16 v[50:65], v[86:89], v[94:97], v[50:65]
	ds_read_b128 v[86:89], v68 offset:4640
	v_mfma_f32_32x32x16_bf16 v[2:17], v[18:21], v[6:9], 0
	v_mfma_f32_32x32x16_bf16 v[18:33], v[18:21], v[22:25], 0
	s_waitcnt lgkmcnt(0)
	v_mfma_f32_32x32x16_bf16 v[2:17], v[86:89], v[90:93], v[2:17]
	ds_read_b128 v[90:93], v1 offset:36928
	v_mfma_f32_32x32x16_bf16 v[18:33], v[86:89], v[94:97], v[18:33]
	ds_read_b128 v[86:89], v68 offset:64
	ds_read_b128 v[94:97], v1 offset:41536
	s_waitcnt lgkmcnt(1)
	v_mfma_f32_32x32x16_bf16 v[34:49], v[86:89], v[90:93], v[34:49]
	s_waitcnt lgkmcnt(0)
	v_mfma_f32_32x32x16_bf16 v[50:65], v[86:89], v[94:97], v[50:65]
	ds_read_b128 v[86:89], v68 offset:4672
	s_waitcnt lgkmcnt(0)
	v_mfma_f32_32x32x16_bf16 v[2:17], v[86:89], v[90:93], v[2:17]
	ds_read_b128 v[90:93], v1 offset:36960
	v_mfma_f32_32x32x16_bf16 v[18:33], v[86:89], v[94:97], v[18:33]
	ds_read_b128 v[86:89], v68 offset:96
	ds_read_b128 v[94:97], v1 offset:41568
	s_waitcnt lgkmcnt(1)
	v_mfma_f32_32x32x16_bf16 v[34:49], v[86:89], v[90:93], v[34:49]
	s_waitcnt lgkmcnt(0)
	v_mfma_f32_32x32x16_bf16 v[50:65], v[86:89], v[94:97], v[50:65]
	v_mfma_f32_32x32x16_bf16 v[2:17], v[98:101], v[90:93], v[2:17]
	v_mfma_f32_32x32x16_bf16 v[18:33], v[98:101], v[94:97], v[18:33]
	s_setprio 0
	s_barrier
; #define MFMA(a, b, c) __builtin_amdgcn_mfma_f32_32x32x16_bf16((a), (b), (c), 0, 0, 0)
; template <int TM, int TN>
; DI void gemm_mainloop(const u16* __restrict__ A, long lda, const u16* __restrict__ Bt, long ldb, int K, char* smem,
;                       f32x16 (&acc)[TM][TN]) {
;     ...
;   for (int kt = 0; kt < nk; kt++) {
;     const int buf = kt & 1;
;     const u16* cA = sA + buf * BM * LD + (wm * 32 * TM + r) * LD + h * 8;
;     const u16* cB = sB + buf * BN * LD + (wn * 32 * TN + r) * LD + h * 8;
;     bf16x8 af[TM], bfr[TN];
; #pragma unroll
;     for (int tm = 0; tm < TM; tm++) af[tm] = *(const bf16x8*)(cA + tm * 32 * LD);
; #pragma unroll
;     for (int tn = 0; tn < TN; tn++) bfr[tn] = *(const bf16x8*)(cB + tn * 32 * LD);
;     if (kt + 1 < nk) GEMM_SSTORE(buf ^ 1)
;     __builtin_amdgcn_sched_barrier(0);
;     __builtin_amdgcn_s_setprio(1);
; #pragma unroll
;     for (int tm = 0; tm < TM; tm++)
; #pragma unroll
;       for (int tn = 0; tn < TN; tn++) acc[tm][tn] = MFMA(af[tm], bfr[tn], acc[tm][tn]);
; #pragma unroll
;     for (int tm = 0; tm < TM; tm++) af[tm] = *(const bf16x8*)(cA + tm * 32 * LD + 16);
; #pragma unroll
;     for (int tn = 0; tn < TN; tn++) bfr[tn] = *(const bf16x8*)(cB + tn * 32 * LD + 16);
; #pragma unroll
;     for (int tm = 0; tm < TM; tm++)
; #pragma unroll
;       for (int tn = 0; tn < TN; tn++) acc[tm][tn] = MFMA(af[tm], bfr[tn], acc[tm][tn]);
;     __builtin_amdgcn_sched_group_barrier(0x8, 4, 0);
;     if (kt + 2 < nk) GEMM_GLOAD((kt + 2) * 64)
; #pragma unroll
;     for (int ks = 2; ks < 4; ks++) {
; #pragma unroll
;       for (int tm = 0; tm < TM; tm++) af[tm] = *(const bf16x8*)(cA + tm * 32 * LD + ks * 16);
; #pragma unroll
;       for (int tn = 0; tn < TN; tn++) bfr[tn] = *(const bf16x8*)(cB + tn * 32 * LD + ks * 16);
; #pragma unroll
;       for (int tm = 0; tm < TM; tm++)
; #pragma unroll
;         for (int tn = 0; tn < TN; tn++) acc[tm][tn] = MFMA(af[tm], bfr[tn], acc[tm][tn]);
;     }
	ds_read_b128 v[94:97], v68 offset:18432
	ds_read_b128 v[98:101], v68 offset:23040
	ds_read_b128 v[126:129], v1 offset:55296
	ds_read_b128 v[130:133], v1 offset:59904
	s_waitcnt vmcnt(1)
	ds_write_b128 v66, v[140:143]
	ds_write_b128 v66, v[102:105] offset:4608
	ds_write_b128 v66, v[106:109] offset:9216
	ds_write_b128 v66, v[110:113] offset:13824
	s_waitcnt vmcnt(0)
	ds_write_b128 v66, v[144:147] offset:36864
	ds_write_b128 v66, v[122:125] offset:41472
	ds_write_b128 v66, v[118:121] offset:46080
	ds_write_b128 v66, v[114:117] offset:50688
	s_setprio 1
	ds_read_b128 v[86:89], v68 offset:18464
	s_waitcnt lgkmcnt(10)
	v_mfma_f32_32x32x16_bf16 v[34:49], v[94:97], v[126:129], v[34:49]
	ds_read_b128 v[90:93], v1 offset:55328
	global_load_dwordx4 v[102:105], v[70:71], off offset:384
	global_load_dwordx4 v[106:109], v[74:75], off offset:384
	global_load_dwordx4 v[110:113], v[78:79], off offset:384
	global_load_dwordx4 v[114:117], v[84:85], off offset:384
	global_load_dwordx4 v[118:121], v[82:83], off offset:384
	global_load_dwordx4 v[122:125], v[80:81], off offset:384
	global_load_dwordx4 v[140:143], v[72:73], off offset:384
	global_load_dwordx4 v[144:147], v[76:77], off offset:384
	s_waitcnt lgkmcnt(10)
	v_mfma_f32_32x32x16_bf16 v[50:65], v[94:97], v[130:133], v[50:65]
	ds_read_b128 v[94:97], v1 offset:59936
	s_waitcnt lgkmcnt(1)
	v_mfma_f32_32x32x16_bf16 v[34:49], v[86:89], v[90:93], v[34:49]
	s_waitcnt lgkmcnt(0)
	v_mfma_f32_32x32x16_bf16 v[50:65], v[86:89], v[94:97], v[50:65]
	ds_read_b128 v[86:89], v68 offset:23072
	v_mfma_f32_32x32x16_bf16 v[2:17], v[98:101], v[126:129], v[2:17]
	v_mfma_f32_32x32x16_bf16 v[18:33], v[98:101], v[130:133], v[18:33]
	ds_read_b128 v[98:101], v68 offset:23136
	s_waitcnt lgkmcnt(1)
	v_mfma_f32_32x32x16_bf16 v[2:17], v[86:89], v[90:93], v[2:17]
	ds_read_b128 v[90:93], v1 offset:55360
	v_mfma_f32_32x32x16_bf16 v[18:33], v[86:89], v[94:97], v[18:33]
	ds_read_b128 v[86:89], v68 offset:18496
	ds_read_b128 v[94:97], v1 offset:59968
	s_waitcnt lgkmcnt(1)
	v_mfma_f32_32x32x16_bf16 v[34:49], v[86:89], v[90:93], v[34:49]
	s_waitcnt lgkmcnt(0)
	v_mfma_f32_32x32x16_bf16 v[50:65], v[86:89], v[94:97], v[50:65]
	ds_read_b128 v[86:89], v68 offset:23104
	s_waitcnt lgkmcnt(0)
	v_mfma_f32_32x32x16_bf16 v[2:17], v[86:89], v[90:93], v[2:17]
	ds_read_b128 v[90:93], v1 offset:55392
	v_mfma_f32_32x32x16_bf16 v[18:33], v[86:89], v[94:97], v[18:33]
	ds_read_b128 v[86:89], v68 offset:18528
	ds_read_b128 v[94:97], v1 offset:60000
	s_waitcnt lgkmcnt(1)
	v_mfma_f32_32x32x16_bf16 v[34:49], v[86:89], v[90:93], v[34:49]
	s_waitcnt lgkmcnt(0)
	v_mfma_f32_32x32x16_bf16 v[50:65], v[86:89], v[94:97], v[50:65]
	v_mfma_f32_32x32x16_bf16 v[2:17], v[98:101], v[90:93], v[2:17]
	v_mfma_f32_32x32x16_bf16 v[18:33], v[98:101], v[94:97], v[18:33]
	s_setprio 0
	s_barrier
	ds_read_b128 v[94:97], v68
	ds_read_b128 v[98:101], v68 offset:4608
	ds_read_b128 v[126:129], v1 offset:36864
	ds_read_b128 v[130:133], v1 offset:41472
	s_waitcnt vmcnt(1)
	ds_write_b128 v66, v[140:143] offset:18432
	ds_write_b128 v66, v[102:105] offset:23040
	ds_write_b128 v66, v[106:109] offset:27648
	ds_write_b128 v66, v[110:113] offset:32256
	s_waitcnt vmcnt(0)
	ds_write_b128 v66, v[144:147] offset:55296
	ds_write_b128 v66, v[122:125] offset:59904
	ds_write_b128 v66, v[118:121] offset:64512
	ds_write_b128 v69, v[114:117] offset:32256
	s_setprio 1
	ds_read_b128 v[86:89], v68 offset:32
	s_waitcnt lgkmcnt(10)
	v_mfma_f32_32x32x16_bf16 v[34:49], v[94:97], v[126:129], v[34:49]
	ds_read_b128 v[90:93], v1 offset:36896
	global_load_dwordx4 v[102:105], v[70:71], off offset:512
	global_load_dwordx4 v[106:109], v[74:75], off offset:512
	global_load_dwordx4 v[110:113], v[78:79], off offset:512
	global_load_dwordx4 v[114:117], v[84:85], off offset:512
	global_load_dwordx4 v[118:121], v[82:83], off offset:512
	global_load_dwordx4 v[122:125], v[80:81], off offset:512
	global_load_dwordx4 v[140:143], v[72:73], off offset:512
	global_load_dwordx4 v[144:147], v[76:77], off offset:512
	s_waitcnt lgkmcnt(10)
	v_mfma_f32_32x32x16_bf16 v[50:65], v[94:97], v[130:133], v[50:65]
	ds_read_b128 v[94:97], v1 offset:41504
	s_waitcnt lgkmcnt(1)
	v_mfma_f32_32x32x16_bf16 v[34:49], v[86:89], v[90:93], v[34:49]
	s_waitcnt lgkmcnt(0)
	v_mfma_f32_32x32x16_bf16 v[50:65], v[86:89], v[94:97], v[50:65]
	ds_read_b128 v[86:89], v68 offset:4640
	v_mfma_f32_32x32x16_bf16 v[2:17], v[98:101], v[126:129], v[2:17]
	v_mfma_f32_32x32x16_bf16 v[18:33], v[98:101], v[130:133], v[18:33]
	ds_read_b128 v[98:101], v68 offset:4704
	s_waitcnt lgkmcnt(1)
	v_mfma_f32_32x32x16_bf16 v[2:17], v[86:89], v[90:93], v[2:17]
	ds_read_b128 v[90:93], v1 offset:36928
	v_mfma_f32_32x32x16_bf16 v[18:33], v[86:89], v[94:97], v[18:33]
	ds_read_b128 v[86:89], v68 offset:64
	ds_read_b128 v[94:97], v1 offset:41536
	s_waitcnt lgkmcnt(1)
	v_mfma_f32_32x32x16_bf16 v[34:49], v[86:89], v[90:93], v[34:49]
	s_waitcnt lgkmcnt(0)
	v_mfma_f32_32x32x16_bf16 v[50:65], v[86:89], v[94:97], v[50:65]
	ds_read_b128 v[86:89], v68 offset:4672
	s_waitcnt lgkmcnt(0)
	v_mfma_f32_32x32x16_bf16 v[2:17], v[86:89], v[90:93], v[2:17]
	ds_read_b128 v[90:93], v1 offset:36960
	v_mfma_f32_32x32x16_bf16 v[18:33], v[86:89], v[94:97], v[18:33]
	ds_read_b128 v[86:89], v68 offset:96
	ds_read_b128 v[94:97], v1 offset:41568
	s_waitcnt lgkmcnt(1)
	v_mfma_f32_32x32x16_bf16 v[34:49], v[86:89], v[90:93], v[34:49]
	s_waitcnt lgkmcnt(0)
	v_mfma_f32_32x32x16_bf16 v[50:65], v[86:89], v[94:97], v[50:65]
	v_mfma_f32_32x32x16_bf16 v[2:17], v[98:101], v[90:93], v[2:17]
	v_mfma_f32_32x32x16_bf16 v[18:33], v[98:101], v[94:97], v[18:33]
	s_setprio 0
	s_barrier
; #define MFMA(a, b, c) __builtin_amdgcn_mfma_f32_32x32x16_bf16((a), (b), (c), 0, 0, 0)
; template <int TM, int TN>
; DI void gemm_mainloop(const u16* __restrict__ A, long lda, const u16* __restrict__ Bt, long ldb, int K, char* smem,
;                       f32x16 (&acc)[TM][TN]) {
;     ...
;   for (int kt = 0; kt < nk; kt++) {
;     const int buf = kt & 1;
;     const u16* cA = sA + buf * BM * LD + (wm * 32 * TM + r) * LD + h * 8;
;     const u16* cB = sB + buf * BN * LD + (wn * 32 * TN + r) * LD + h * 8;
;     bf16x8 af[TM], bfr[TN];
; #pragma unroll
;     for (int tm = 0; tm < TM; tm++) af[tm] = *(const bf16x8*)(cA + tm * 32 * LD);
; #pragma unroll
;     for (int tn = 0; tn < TN; tn++) bfr[tn] = *(const bf16x8*)(cB + tn * 32 * LD);
;     if (kt + 1 < nk) GEMM_SSTORE(buf ^ 1)
;     __builtin_amdgcn_sched_barrier(0);
;     __builtin_amdgcn_s_setprio(1);
; #pragma unroll
;     for (int tm = 0; tm < TM; tm++)
; #pragma unroll
;       for (int tn = 0; tn < TN; tn++) acc[tm][tn] = MFMA(af[tm], bfr[tn], acc[tm][tn]);
; #pragma unroll
;     for (int tm = 0; tm < TM; tm++) af[tm] = *(const bf16x8*)(cA + tm * 32 * LD + 16);
; #pragma unroll
;     for (int tn = 0; tn < TN; tn++) bfr[tn] = *(const bf16x8*)(cB + tn * 32 * LD + 16);
; #pragma unroll
;     for (int tm = 0; tm < TM; tm++)
; #pragma unroll
;       for (int tn = 0; tn < TN; tn++) acc[tm][tn] = MFMA(af[tm], bfr[tn], acc[tm][tn]);
;     __builtin_amdgcn_sched_group_barrier(0x8, 4, 0);
;     if (kt + 2 < nk) GEMM_GLOAD((kt + 2) * 64)
; #pragma unroll
;     for (int ks = 2; ks < 4; ks++) {
; #pragma unroll
;       for (int tm = 0; tm < TM; tm++) af[tm] = *(const bf16x8*)(cA + tm * 32 * LD + ks * 16);
; #pragma unroll
;       for (int tn = 0; tn < TN; tn++) bfr[tn] = *(const bf16x8*)(cB + tn * 32 * LD + ks * 16);
; #pragma unroll
;       for (int tm = 0; tm < TM; tm++)
; #pragma unroll
;         for (int tn = 0; tn < TN; tn++) acc[tm][tn] = MFMA(af[tm], bfr[tn], acc[tm][tn]);
;     }
	ds_read_b128 v[94:97], v68 offset:18432
	ds_read_b128 v[98:101], v68 offset:23040
	ds_read_b128 v[126:129], v1 offset:55296
	ds_read_b128 v[130:133], v1 offset:59904
	s_waitcnt vmcnt(1)
	ds_write_b128 v66, v[140:143]
	ds_write_b128 v66, v[102:105] offset:4608
	ds_write_b128 v66, v[106:109] offset:9216
	ds_write_b128 v66, v[110:113] offset:13824
	s_waitcnt vmcnt(0)
	ds_write_b128 v66, v[144:147] offset:36864
	ds_write_b128 v66, v[122:125] offset:41472
	ds_write_b128 v66, v[118:121] offset:46080
	ds_write_b128 v66, v[114:117] offset:50688
	s_setprio 1
	ds_read_b128 v[86:89], v68 offset:18464
	s_waitcnt lgkmcnt(10)
	v_mfma_f32_32x32x16_bf16 v[34:49], v[94:97], v[126:129], v[34:49]
	ds_read_b128 v[90:93], v1 offset:55328
	global_load_dwordx4 v[102:105], v[70:71], off offset:640
	global_load_dwordx4 v[106:109], v[74:75], off offset:640
	global_load_dwordx4 v[110:113], v[78:79], off offset:640
	global_load_dwordx4 v[114:117], v[84:85], off offset:640
	global_load_dwordx4 v[118:121], v[82:83], off offset:640
	global_load_dwordx4 v[122:125], v[80:81], off offset:640
	global_load_dwordx4 v[140:143], v[72:73], off offset:640
	global_load_dwordx4 v[144:147], v[76:77], off offset:640
	s_waitcnt lgkmcnt(10)
	v_mfma_f32_32x32x16_bf16 v[50:65], v[94:97], v[130:133], v[50:65]
	ds_read_b128 v[94:97], v1 offset:59936
	s_waitcnt lgkmcnt(1)
	v_mfma_f32_32x32x16_bf16 v[34:49], v[86:89], v[90:93], v[34:49]
	s_waitcnt lgkmcnt(0)
	v_mfma_f32_32x32x16_bf16 v[50:65], v[86:89], v[94:97], v[50:65]
	ds_read_b128 v[86:89], v68 offset:23072
	v_mfma_f32_32x32x16_bf16 v[2:17], v[98:101], v[126:129], v[2:17]
	v_mfma_f32_32x32x16_bf16 v[18:33], v[98:101], v[130:133], v[18:33]
	ds_read_b128 v[98:101], v68 offset:23136
	s_waitcnt lgkmcnt(1)
	v_mfma_f32_32x32x16_bf16 v[2:17], v[86:89], v[90:93], v[2:17]
	ds_read_b128 v[90:93], v1 offset:55360
	v_mfma_f32_32x32x16_bf16 v[18:33], v[86:89], v[94:97], v[18:33]
	ds_read_b128 v[86:89], v68 offset:18496
	ds_read_b128 v[94:97], v1 offset:59968
	s_waitcnt lgkmcnt(1)
	v_mfma_f32_32x32x16_bf16 v[34:49], v[86:89], v[90:93], v[34:49]
	s_waitcnt lgkmcnt(0)
	v_mfma_f32_32x32x16_bf16 v[50:65], v[86:89], v[94:97], v[50:65]
	ds_read_b128 v[86:89], v68 offset:23104
	s_waitcnt lgkmcnt(0)
	v_mfma_f32_32x32x16_bf16 v[2:17], v[86:89], v[90:93], v[2:17]
	ds_read_b128 v[90:93], v1 offset:55392
	v_mfma_f32_32x32x16_bf16 v[18:33], v[86:89], v[94:97], v[18:33]
	ds_read_b128 v[86:89], v68 offset:18528
	ds_read_b128 v[94:97], v1 offset:60000
	s_waitcnt lgkmcnt(1)
	v_mfma_f32_32x32x16_bf16 v[34:49], v[86:89], v[90:93], v[34:49]
	s_waitcnt lgkmcnt(0)
	v_mfma_f32_32x32x16_bf16 v[50:65], v[86:89], v[94:97], v[50:65]
	v_mfma_f32_32x32x16_bf16 v[2:17], v[98:101], v[90:93], v[2:17]
	v_mfma_f32_32x32x16_bf16 v[18:33], v[98:101], v[94:97], v[18:33]
	s_setprio 0
	s_barrier
	ds_read_b128 v[94:97], v68
	ds_read_b128 v[98:101], v68 offset:4608
	ds_read_b128 v[126:129], v1 offset:36864
	ds_read_b128 v[130:133], v1 offset:41472
	s_waitcnt vmcnt(1)
	ds_write_b128 v66, v[140:143] offset:18432
	ds_write_b128 v66, v[102:105] offset:23040
	ds_write_b128 v66, v[106:109] offset:27648
	ds_write_b128 v66, v[110:113] offset:32256
	s_waitcnt vmcnt(0)
	ds_write_b128 v66, v[144:147] offset:55296
	ds_write_b128 v66, v[122:125] offset:59904
	ds_write_b128 v66, v[118:121] offset:64512
	ds_write_b128 v69, v[114:117] offset:32256
	s_setprio 1
	ds_read_b128 v[86:89], v68 offset:32
	s_waitcnt lgkmcnt(10)
	v_mfma_f32_32x32x16_bf16 v[34:49], v[94:97], v[126:129], v[34:49]
	ds_read_b128 v[90:93], v1 offset:36896
	global_load_dwordx4 v[102:105], v[70:71], off offset:768
	global_load_dwordx4 v[106:109], v[74:75], off offset:768
	global_load_dwordx4 v[110:113], v[78:79], off offset:768
	global_load_dwordx4 v[114:117], v[84:85], off offset:768
	global_load_dwordx4 v[118:121], v[82:83], off offset:768
	global_load_dwordx4 v[122:125], v[80:81], off offset:768
	global_load_dwordx4 v[140:143], v[72:73], off offset:768
	global_load_dwordx4 v[144:147], v[76:77], off offset:768
	s_waitcnt lgkmcnt(10)
	v_mfma_f32_32x32x16_bf16 v[50:65], v[94:97], v[130:133], v[50:65]
	ds_read_b128 v[94:97], v1 offset:41504
	s_waitcnt lgkmcnt(1)
	v_mfma_f32_32x32x16_bf16 v[34:49], v[86:89], v[90:93], v[34:49]
	s_waitcnt lgkmcnt(0)
	v_mfma_f32_32x32x16_bf16 v[50:65], v[86:89], v[94:97], v[50:65]
	ds_read_b128 v[86:89], v68 offset:4640
	v_mfma_f32_32x32x16_bf16 v[2:17], v[98:101], v[126:129], v[2:17]
	v_mfma_f32_32x32x16_bf16 v[18:33], v[98:101], v[130:133], v[18:33]
	ds_read_b128 v[98:101], v68 offset:4704
	s_waitcnt lgkmcnt(1)
	v_mfma_f32_32x32x16_bf16 v[2:17], v[86:89], v[90:93], v[2:17]
	ds_read_b128 v[90:93], v1 offset:36928
	v_mfma_f32_32x32x16_bf16 v[18:33], v[86:89], v[94:97], v[18:33]
	ds_read_b128 v[86:89], v68 offset:64
	ds_read_b128 v[94:97], v1 offset:41536
	s_waitcnt lgkmcnt(1)
	v_mfma_f32_32x32x16_bf16 v[34:49], v[86:89], v[90:93], v[34:49]
	s_waitcnt lgkmcnt(0)
	v_mfma_f32_32x32x16_bf16 v[50:65], v[86:89], v[94:97], v[50:65]
	ds_read_b128 v[86:89], v68 offset:4672
	s_waitcnt lgkmcnt(0)
	v_mfma_f32_32x32x16_bf16 v[2:17], v[86:89], v[90:93], v[2:17]
	ds_read_b128 v[90:93], v1 offset:36960
	v_mfma_f32_32x32x16_bf16 v[18:33], v[86:89], v[94:97], v[18:33]
	ds_read_b128 v[86:89], v68 offset:96
	ds_read_b128 v[94:97], v1 offset:41568
	s_waitcnt lgkmcnt(1)
	v_mfma_f32_32x32x16_bf16 v[34:49], v[86:89], v[90:93], v[34:49]
	s_waitcnt lgkmcnt(0)
	v_mfma_f32_32x32x16_bf16 v[50:65], v[86:89], v[94:97], v[50:65]
	v_mfma_f32_32x32x16_bf16 v[2:17], v[98:101], v[90:93], v[2:17]
	v_mfma_f32_32x32x16_bf16 v[18:33], v[98:101], v[94:97], v[18:33]
	s_setprio 0
	s_barrier
; #define MFMA(a, b, c) __builtin_amdgcn_mfma_f32_32x32x16_bf16((a), (b), (c), 0, 0, 0)
; template <int TM, int TN>
; DI void gemm_mainloop(const u16* __restrict__ A, long lda, const u16* __restrict__ Bt, long ldb, int K, char* smem,
;                       f32x16 (&acc)[TM][TN]) {
;     ...
;   for (int kt = 0; kt < nk; kt++) {
;     const int buf = kt & 1;
;     const u16* cA = sA + buf * BM * LD + (wm * 32 * TM + r) * LD + h * 8;
;     const u16* cB = sB + buf * BN * LD + (wn * 32 * TN + r) * LD + h * 8;
;     bf16x8 af[TM], bfr[TN];
; #pragma unroll
;     for (int tm = 0; tm < TM; tm++) af[tm] = *(const bf16x8*)(cA + tm * 32 * LD);
; #pragma unroll
;     for (int tn = 0; tn < TN; tn++) bfr[tn] = *(const bf16x8*)(cB + tn * 32 * LD);
;     if (kt + 1 < nk) GEMM_SSTORE(buf ^ 1)
;     __builtin_amdgcn_sched_barrier(0);
;     __builtin_amdgcn_s_setprio(1);
; #pragma unroll
;     for (int tm = 0; tm < TM; tm++)
; #pragma unroll
;       for (int tn = 0; tn < TN; tn++) acc[tm][tn] = MFMA(af[tm], bfr[tn], acc[tm][tn]);
; #pragma unroll
;     for (int tm = 0; tm < TM; tm++) af[tm] = *(const bf16x8*)(cA + tm * 32 * LD + 16);
; #pragma unroll
;     for (int tn = 0; tn < TN; tn++) bfr[tn] = *(const bf16x8*)(cB + tn * 32 * LD + 16);
; #pragma unroll
;     for (int tm = 0; tm < TM; tm++)
; #pragma unroll
;       for (int tn = 0; tn < TN; tn++) acc[tm][tn] = MFMA(af[tm], bfr[tn], acc[tm][tn]);
;     __builtin_amdgcn_sched_group_barrier(0x8, 4, 0);
;     if (kt + 2 < nk) GEMM_GLOAD((kt + 2) * 64)
; #pragma unroll
;     for (int ks = 2; ks < 4; ks++) {
; #pragma unroll
;       for (int tm = 0; tm < TM; tm++) af[tm] = *(const bf16x8*)(cA + tm * 32 * LD + ks * 16);
; #pragma unroll
;       for (int tn = 0; tn < TN; tn++) bfr[tn] = *(const bf16x8*)(cB + tn * 32 * LD + ks * 16);
; #pragma unroll
;       for (int tm = 0; tm < TM; tm++)
; #pragma unroll
;         for (int tn = 0; tn < TN; tn++) acc[tm][tn] = MFMA(af[tm], bfr[tn], acc[tm][tn]);
;     }
	ds_read_b128 v[94:97], v68 offset:18432
	ds_read_b128 v[98:101], v68 offset:23040
	ds_read_b128 v[126:129], v1 offset:55296
	ds_read_b128 v[130:133], v1 offset:59904
	s_waitcnt vmcnt(1)
	ds_write_b128 v66, v[140:143]
	ds_write_b128 v66, v[102:105] offset:4608
	ds_write_b128 v66, v[106:109] offset:9216
	ds_write_b128 v66, v[110:113] offset:13824
	s_waitcnt vmcnt(0)
	ds_write_b128 v66, v[144:147] offset:36864
	ds_write_b128 v66, v[122:125] offset:41472
	ds_write_b128 v66, v[118:121] offset:46080
	ds_write_b128 v66, v[114:117] offset:50688
	s_setprio 1
	ds_read_b128 v[86:89], v68 offset:18464
	s_waitcnt lgkmcnt(10)
	v_mfma_f32_32x32x16_bf16 v[34:49], v[94:97], v[126:129], v[34:49]
	ds_read_b128 v[90:93], v1 offset:55328
	global_load_dwordx4 v[102:105], v[70:71], off offset:896
	global_load_dwordx4 v[106:109], v[74:75], off offset:896
	global_load_dwordx4 v[110:113], v[78:79], off offset:896
	global_load_dwordx4 v[114:117], v[84:85], off offset:896
	global_load_dwordx4 v[118:121], v[82:83], off offset:896
	global_load_dwordx4 v[122:125], v[80:81], off offset:896
	global_load_dwordx4 v[140:143], v[72:73], off offset:896
	global_load_dwordx4 v[144:147], v[76:77], off offset:896
	s_waitcnt lgkmcnt(10)
	v_mfma_f32_32x32x16_bf16 v[50:65], v[94:97], v[130:133], v[50:65]
	ds_read_b128 v[94:97], v1 offset:59936
	s_waitcnt lgkmcnt(1)
	v_mfma_f32_32x32x16_bf16 v[34:49], v[86:89], v[90:93], v[34:49]
	s_waitcnt lgkmcnt(0)
	v_mfma_f32_32x32x16_bf16 v[50:65], v[86:89], v[94:97], v[50:65]
	ds_read_b128 v[86:89], v68 offset:23072
	v_mfma_f32_32x32x16_bf16 v[2:17], v[98:101], v[126:129], v[2:17]
	v_mfma_f32_32x32x16_bf16 v[18:33], v[98:101], v[130:133], v[18:33]
	ds_read_b128 v[98:101], v68 offset:23136
	s_waitcnt lgkmcnt(1)
	v_mfma_f32_32x32x16_bf16 v[2:17], v[86:89], v[90:93], v[2:17]
	ds_read_b128 v[90:93], v1 offset:55360
	v_mfma_f32_32x32x16_bf16 v[18:33], v[86:89], v[94:97], v[18:33]
	ds_read_b128 v[86:89], v68 offset:18496
	ds_read_b128 v[94:97], v1 offset:59968
	s_waitcnt lgkmcnt(1)
	v_mfma_f32_32x32x16_bf16 v[34:49], v[86:89], v[90:93], v[34:49]
	s_waitcnt lgkmcnt(0)
	v_mfma_f32_32x32x16_bf16 v[50:65], v[86:89], v[94:97], v[50:65]
	ds_read_b128 v[86:89], v68 offset:23104
	s_waitcnt lgkmcnt(0)
	v_mfma_f32_32x32x16_bf16 v[2:17], v[86:89], v[90:93], v[2:17]
	ds_read_b128 v[90:93], v1 offset:55392
	v_mfma_f32_32x32x16_bf16 v[18:33], v[86:89], v[94:97], v[18:33]
	ds_read_b128 v[86:89], v68 offset:18528
	ds_read_b128 v[94:97], v1 offset:60000
	s_waitcnt lgkmcnt(1)
	v_mfma_f32_32x32x16_bf16 v[34:49], v[86:89], v[90:93], v[34:49]
	s_waitcnt lgkmcnt(0)
	v_mfma_f32_32x32x16_bf16 v[50:65], v[86:89], v[94:97], v[50:65]
	v_mfma_f32_32x32x16_bf16 v[2:17], v[98:101], v[90:93], v[2:17]
	v_mfma_f32_32x32x16_bf16 v[18:33], v[98:101], v[94:97], v[18:33]
	s_setprio 0
	s_barrier
	ds_read_b128 v[94:97], v68
	ds_read_b128 v[98:101], v68 offset:4608
	ds_read_b128 v[126:129], v1 offset:36864
	ds_read_b128 v[130:133], v1 offset:41472
	s_waitcnt vmcnt(1)
	ds_write_b128 v66, v[140:143] offset:18432
	ds_write_b128 v66, v[102:105] offset:23040
	ds_write_b128 v66, v[106:109] offset:27648
	ds_write_b128 v66, v[110:113] offset:32256
	s_waitcnt vmcnt(0)
	ds_write_b128 v66, v[144:147] offset:55296
	ds_write_b128 v66, v[122:125] offset:59904
	ds_write_b128 v66, v[118:121] offset:64512
	ds_write_b128 v69, v[114:117] offset:32256
	s_setprio 1
	ds_read_b128 v[86:89], v68 offset:32
	s_waitcnt lgkmcnt(10)
	v_mfma_f32_32x32x16_bf16 v[34:49], v[94:97], v[126:129], v[34:49]
	ds_read_b128 v[90:93], v1 offset:36896
	global_load_dwordx4 v[102:105], v[70:71], off offset:1024
	global_load_dwordx4 v[106:109], v[74:75], off offset:1024
	global_load_dwordx4 v[110:113], v[78:79], off offset:1024
	global_load_dwordx4 v[114:117], v[84:85], off offset:1024
	global_load_dwordx4 v[118:121], v[82:83], off offset:1024
	global_load_dwordx4 v[122:125], v[80:81], off offset:1024
	global_load_dwordx4 v[140:143], v[72:73], off offset:1024
	global_load_dwordx4 v[144:147], v[76:77], off offset:1024
	s_waitcnt lgkmcnt(10)
	v_mfma_f32_32x32x16_bf16 v[50:65], v[94:97], v[130:133], v[50:65]
	ds_read_b128 v[94:97], v1 offset:41504
	s_waitcnt lgkmcnt(1)
	v_mfma_f32_32x32x16_bf16 v[34:49], v[86:89], v[90:93], v[34:49]
	s_waitcnt lgkmcnt(0)
	v_mfma_f32_32x32x16_bf16 v[50:65], v[86:89], v[94:97], v[50:65]
	ds_read_b128 v[86:89], v68 offset:4640
	v_mfma_f32_32x32x16_bf16 v[2:17], v[98:101], v[126:129], v[2:17]
	v_mfma_f32_32x32x16_bf16 v[18:33], v[98:101], v[130:133], v[18:33]
	ds_read_b128 v[98:101], v68 offset:4704
	s_waitcnt lgkmcnt(1)
	v_mfma_f32_32x32x16_bf16 v[2:17], v[86:89], v[90:93], v[2:17]
	ds_read_b128 v[90:93], v1 offset:36928
	v_mfma_f32_32x32x16_bf16 v[18:33], v[86:89], v[94:97], v[18:33]
	ds_read_b128 v[86:89], v68 offset:64
	ds_read_b128 v[94:97], v1 offset:41536
	s_waitcnt lgkmcnt(1)
	v_mfma_f32_32x32x16_bf16 v[34:49], v[86:89], v[90:93], v[34:49]
	s_waitcnt lgkmcnt(0)
	v_mfma_f32_32x32x16_bf16 v[50:65], v[86:89], v[94:97], v[50:65]
	ds_read_b128 v[86:89], v68 offset:4672
	s_waitcnt lgkmcnt(0)
	v_mfma_f32_32x32x16_bf16 v[2:17], v[86:89], v[90:93], v[2:17]
	ds_read_b128 v[90:93], v1 offset:36960
	v_mfma_f32_32x32x16_bf16 v[18:33], v[86:89], v[94:97], v[18:33]
	ds_read_b128 v[86:89], v68 offset:96
	ds_read_b128 v[94:97], v1 offset:41568
	s_waitcnt lgkmcnt(1)
	v_mfma_f32_32x32x16_bf16 v[34:49], v[86:89], v[90:93], v[34:49]
	s_waitcnt lgkmcnt(0)
	v_mfma_f32_32x32x16_bf16 v[50:65], v[86:89], v[94:97], v[50:65]
	v_mfma_f32_32x32x16_bf16 v[2:17], v[98:101], v[90:93], v[2:17]
	v_mfma_f32_32x32x16_bf16 v[18:33], v[98:101], v[94:97], v[18:33]
	s_setprio 0
	s_barrier
; #define MFMA(a, b, c) __builtin_amdgcn_mfma_f32_32x32x16_bf16((a), (b), (c), 0, 0, 0)
; template <int TM, int TN>
; DI void gemm_mainloop(const u16* __restrict__ A, long lda, const u16* __restrict__ Bt, long ldb, int K, char* smem,
;                       f32x16 (&acc)[TM][TN]) {
;     ...
;   for (int kt = 0; kt < nk; kt++) {
;     const int buf = kt & 1;
;     const u16* cA = sA + buf * BM * LD + (wm * 32 * TM + r) * LD + h * 8;
;     const u16* cB = sB + buf * BN * LD + (wn * 32 * TN + r) * LD + h * 8;
;     bf16x8 af[TM], bfr[TN];
; #pragma unroll
;     for (int tm = 0; tm < TM; tm++) af[tm] = *(const bf16x8*)(cA + tm * 32 * LD);
; #pragma unroll
;     for (int tn = 0; tn < TN; tn++) bfr[tn] = *(const bf16x8*)(cB + tn * 32 * LD);
;     if (kt + 1 < nk) GEMM_SSTORE(buf ^ 1)
;     __builtin_amdgcn_sched_barrier(0);
;     __builtin_amdgcn_s_setprio(1);
; #pragma unroll
;     for (int tm = 0; tm < TM; tm++)
; #pragma unroll
;       for (int tn = 0; tn < TN; tn++) acc[tm][tn] = MFMA(af[tm], bfr[tn], acc[tm][tn]);
; #pragma unroll
;     for (int tm = 0; tm < TM; tm++) af[tm] = *(const bf16x8*)(cA + tm * 32 * LD + 16);
; #pragma unroll
;     for (int tn = 0; tn < TN; tn++) bfr[tn] = *(const bf16x8*)(cB + tn * 32 * LD + 16);
; #pragma unroll
;     for (int tm = 0; tm < TM; tm++)
; #pragma unroll
;       for (int tn = 0; tn < TN; tn++) acc[tm][tn] = MFMA(af[tm], bfr[tn], acc[tm][tn]);
;     __builtin_amdgcn_sched_group_barrier(0x8, 4, 0);
;     if (kt + 2 < nk) GEMM_GLOAD((kt + 2) * 64)
; #pragma unroll
;     for (int ks = 2; ks < 4; ks++) {
; #pragma unroll
;       for (int tm = 0; tm < TM; tm++) af[tm] = *(const bf16x8*)(cA + tm * 32 * LD + ks * 16);
; #pragma unroll
;       for (int tn = 0; tn < TN; tn++) bfr[tn] = *(const bf16x8*)(cB + tn * 32 * LD + ks * 16);
; #pragma unroll
;       for (int tm = 0; tm < TM; tm++)
; #pragma unroll
;         for (int tn = 0; tn < TN; tn++) acc[tm][tn] = MFMA(af[tm], bfr[tn], acc[tm][tn]);
;     }
	ds_read_b128 v[94:97], v68 offset:18432
	ds_read_b128 v[98:101], v68 offset:23040
	ds_read_b128 v[126:129], v1 offset:55296
	ds_read_b128 v[130:133], v1 offset:59904
	s_waitcnt vmcnt(1)
	ds_write_b128 v66, v[140:143]
	ds_write_b128 v66, v[102:105] offset:4608
	ds_write_b128 v66, v[106:109] offset:9216
	ds_write_b128 v66, v[110:113] offset:13824
	s_waitcnt vmcnt(0)
	ds_write_b128 v66, v[144:147] offset:36864
	ds_write_b128 v66, v[122:125] offset:41472
	ds_write_b128 v66, v[118:121] offset:46080
	ds_write_b128 v66, v[114:117] offset:50688
	s_setprio 1
	ds_read_b128 v[86:89], v68 offset:18464
	s_waitcnt lgkmcnt(10)
	v_mfma_f32_32x32x16_bf16 v[34:49], v[94:97], v[126:129], v[34:49]
	ds_read_b128 v[90:93], v1 offset:55328
	global_load_dwordx4 v[102:105], v[70:71], off offset:1152
	global_load_dwordx4 v[106:109], v[74:75], off offset:1152
	global_load_dwordx4 v[110:113], v[78:79], off offset:1152
	global_load_dwordx4 v[114:117], v[84:85], off offset:1152
	global_load_dwordx4 v[118:121], v[82:83], off offset:1152
	global_load_dwordx4 v[122:125], v[80:81], off offset:1152
	global_load_dwordx4 v[140:143], v[72:73], off offset:1152
	global_load_dwordx4 v[144:147], v[76:77], off offset:1152
	s_waitcnt lgkmcnt(10)
	v_mfma_f32_32x32x16_bf16 v[50:65], v[94:97], v[130:133], v[50:65]
	ds_read_b128 v[94:97], v1 offset:59936
	s_waitcnt lgkmcnt(1)
	v_mfma_f32_32x32x16_bf16 v[34:49], v[86:89], v[90:93], v[34:49]
	s_waitcnt lgkmcnt(0)
	v_mfma_f32_32x32x16_bf16 v[50:65], v[86:89], v[94:97], v[50:65]
	ds_read_b128 v[86:89], v68 offset:23072
	v_mfma_f32_32x32x16_bf16 v[2:17], v[98:101], v[126:129], v[2:17]
	v_mfma_f32_32x32x16_bf16 v[18:33], v[98:101], v[130:133], v[18:33]
	ds_read_b128 v[98:101], v68 offset:23136
	s_waitcnt lgkmcnt(1)
	v_mfma_f32_32x32x16_bf16 v[2:17], v[86:89], v[90:93], v[2:17]
	ds_read_b128 v[90:93], v1 offset:55360
	v_mfma_f32_32x32x16_bf16 v[18:33], v[86:89], v[94:97], v[18:33]
	ds_read_b128 v[86:89], v68 offset:18496
	ds_read_b128 v[94:97], v1 offset:59968
	s_waitcnt lgkmcnt(1)
	v_mfma_f32_32x32x16_bf16 v[34:49], v[86:89], v[90:93], v[34:49]
	s_waitcnt lgkmcnt(0)
	v_mfma_f32_32x32x16_bf16 v[50:65], v[86:89], v[94:97], v[50:65]
	ds_read_b128 v[86:89], v68 offset:23104
	s_waitcnt lgkmcnt(0)
	v_mfma_f32_32x32x16_bf16 v[2:17], v[86:89], v[90:93], v[2:17]
	ds_read_b128 v[90:93], v1 offset:55392
	v_mfma_f32_32x32x16_bf16 v[18:33], v[86:89], v[94:97], v[18:33]
	ds_read_b128 v[86:89], v68 offset:18528
	ds_read_b128 v[94:97], v1 offset:60000
	s_waitcnt lgkmcnt(1)
	v_mfma_f32_32x32x16_bf16 v[34:49], v[86:89], v[90:93], v[34:49]
	s_waitcnt lgkmcnt(0)
	v_mfma_f32_32x32x16_bf16 v[50:65], v[86:89], v[94:97], v[50:65]
	v_mfma_f32_32x32x16_bf16 v[2:17], v[98:101], v[90:93], v[2:17]
	v_mfma_f32_32x32x16_bf16 v[18:33], v[98:101], v[94:97], v[18:33]
	s_setprio 0
	s_barrier
	ds_read_b128 v[94:97], v68
	ds_read_b128 v[98:101], v68 offset:4608
	ds_read_b128 v[126:129], v1 offset:36864
	ds_read_b128 v[130:133], v1 offset:41472
	s_waitcnt vmcnt(1)
	ds_write_b128 v66, v[140:143] offset:18432
	ds_write_b128 v66, v[102:105] offset:23040
	ds_write_b128 v66, v[106:109] offset:27648
	ds_write_b128 v66, v[110:113] offset:32256
	s_waitcnt vmcnt(0)
	ds_write_b128 v66, v[144:147] offset:55296
	ds_write_b128 v66, v[122:125] offset:59904
	ds_write_b128 v66, v[118:121] offset:64512
	ds_write_b128 v69, v[114:117] offset:32256
	s_setprio 1
	ds_read_b128 v[86:89], v68 offset:32
	s_waitcnt lgkmcnt(10)
	v_mfma_f32_32x32x16_bf16 v[34:49], v[94:97], v[126:129], v[34:49]
	ds_read_b128 v[90:93], v1 offset:36896
	global_load_dwordx4 v[102:105], v[70:71], off offset:1280
	global_load_dwordx4 v[106:109], v[74:75], off offset:1280
	global_load_dwordx4 v[110:113], v[78:79], off offset:1280
	global_load_dwordx4 v[114:117], v[84:85], off offset:1280
	global_load_dwordx4 v[118:121], v[82:83], off offset:1280
	global_load_dwordx4 v[122:125], v[80:81], off offset:1280
	global_load_dwordx4 v[140:143], v[72:73], off offset:1280
	global_load_dwordx4 v[144:147], v[76:77], off offset:1280
	s_waitcnt lgkmcnt(10)
	v_mfma_f32_32x32x16_bf16 v[50:65], v[94:97], v[130:133], v[50:65]
	ds_read_b128 v[94:97], v1 offset:41504
	s_waitcnt lgkmcnt(1)
	v_mfma_f32_32x32x16_bf16 v[34:49], v[86:89], v[90:93], v[34:49]
	s_waitcnt lgkmcnt(0)
	v_mfma_f32_32x32x16_bf16 v[50:65], v[86:89], v[94:97], v[50:65]
	ds_read_b128 v[86:89], v68 offset:4640
	v_mfma_f32_32x32x16_bf16 v[2:17], v[98:101], v[126:129], v[2:17]
	v_mfma_f32_32x32x16_bf16 v[18:33], v[98:101], v[130:133], v[18:33]
	ds_read_b128 v[98:101], v68 offset:4704
	s_waitcnt lgkmcnt(1)
	v_mfma_f32_32x32x16_bf16 v[2:17], v[86:89], v[90:93], v[2:17]
	ds_read_b128 v[90:93], v1 offset:36928
	v_mfma_f32_32x32x16_bf16 v[18:33], v[86:89], v[94:97], v[18:33]
	ds_read_b128 v[86:89], v68 offset:64
	ds_read_b128 v[94:97], v1 offset:41536
	s_waitcnt lgkmcnt(1)
	v_mfma_f32_32x32x16_bf16 v[34:49], v[86:89], v[90:93], v[34:49]
	s_waitcnt lgkmcnt(0)
	v_mfma_f32_32x32x16_bf16 v[50:65], v[86:89], v[94:97], v[50:65]
	ds_read_b128 v[86:89], v68 offset:4672
	s_waitcnt lgkmcnt(0)
	v_mfma_f32_32x32x16_bf16 v[2:17], v[86:89], v[90:93], v[2:17]
	ds_read_b128 v[90:93], v1 offset:36960
	v_mfma_f32_32x32x16_bf16 v[18:33], v[86:89], v[94:97], v[18:33]
	ds_read_b128 v[86:89], v68 offset:96
	ds_read_b128 v[94:97], v1 offset:41568
	s_waitcnt lgkmcnt(1)
	v_mfma_f32_32x32x16_bf16 v[34:49], v[86:89], v[90:93], v[34:49]
	s_waitcnt lgkmcnt(0)
	v_mfma_f32_32x32x16_bf16 v[50:65], v[86:89], v[94:97], v[50:65]
	v_mfma_f32_32x32x16_bf16 v[2:17], v[98:101], v[90:93], v[2:17]
	v_mfma_f32_32x32x16_bf16 v[18:33], v[98:101], v[94:97], v[18:33]
	s_setprio 0
	s_barrier
; #define MFMA(a, b, c) __builtin_amdgcn_mfma_f32_32x32x16_bf16((a), (b), (c), 0, 0, 0)
; template <int TM, int TN>
; DI void gemm_mainloop(const u16* __restrict__ A, long lda, const u16* __restrict__ Bt, long ldb, int K, char* smem,
;                       f32x16 (&acc)[TM][TN]) {
;     ...
;   for (int kt = 0; kt < nk; kt++) {
;     const int buf = kt & 1;
;     const u16* cA = sA + buf * BM * LD + (wm * 32 * TM + r) * LD + h * 8;
;     const u16* cB = sB + buf * BN * LD + (wn * 32 * TN + r) * LD + h * 8;
;     bf16x8 af[TM], bfr[TN];
; #pragma unroll
;     for (int tm = 0; tm < TM; tm++) af[tm] = *(const bf16x8*)(cA + tm * 32 * LD);
; #pragma unroll
;     for (int tn = 0; tn < TN; tn++) bfr[tn] = *(const bf16x8*)(cB + tn * 32 * LD);
;     if (kt + 1 < nk) GEMM_SSTORE(buf ^ 1)
;     __builtin_amdgcn_sched_barrier(0);
;     __builtin_amdgcn_s_setprio(1);
; #pragma unroll
;     for (int tm = 0; tm < TM; tm++)
; #pragma unroll
;       for (int tn = 0; tn < TN; tn++) acc[tm][tn] = MFMA(af[tm], bfr[tn], acc[tm][tn]);
; #pragma unroll
;     for (int tm = 0; tm < TM; tm++) af[tm] = *(const bf16x8*)(cA + tm * 32 * LD + 16);
; #pragma unroll
;     for (int tn = 0; tn < TN; tn++) bfr[tn] = *(const bf16x8*)(cB + tn * 32 * LD + 16);
; #pragma unroll
;     for (int tm = 0; tm < TM; tm++)
; #pragma unroll
;       for (int tn = 0; tn < TN; tn++) acc[tm][tn] = MFMA(af[tm], bfr[tn], acc[tm][tn]);
;     __builtin_amdgcn_sched_group_barrier(0x8, 4, 0);
;     if (kt + 2 < nk) GEMM_GLOAD((kt + 2) * 64)
; #pragma unroll
;     for (int ks = 2; ks < 4; ks++) {
; #pragma unroll
;       for (int tm = 0; tm < TM; tm++) af[tm] = *(const bf16x8*)(cA + tm * 32 * LD + ks * 16);
; #pragma unroll
;       for (int tn = 0; tn < TN; tn++) bfr[tn] = *(const bf16x8*)(cB + tn * 32 * LD + ks * 16);
; #pragma unroll
;       for (int tm = 0; tm < TM; tm++)
; #pragma unroll
;         for (int tn = 0; tn < TN; tn++) acc[tm][tn] = MFMA(af[tm], bfr[tn], acc[tm][tn]);
;     }
	ds_read_b128 v[94:97], v68 offset:18432
	ds_read_b128 v[98:101], v68 offset:23040
	ds_read_b128 v[126:129], v1 offset:55296
	ds_read_b128 v[130:133], v1 offset:59904
	s_waitcnt vmcnt(1)
	ds_write_b128 v66, v[140:143]
	ds_write_b128 v66, v[102:105] offset:4608
	ds_write_b128 v66, v[106:109] offset:9216
	ds_write_b128 v66, v[110:113] offset:13824
	s_waitcnt vmcnt(0)
	ds_write_b128 v66, v[144:147] offset:36864
	ds_write_b128 v66, v[122:125] offset:41472
	ds_write_b128 v66, v[118:121] offset:46080
	ds_write_b128 v66, v[114:117] offset:50688
	s_setprio 1
	ds_read_b128 v[86:89], v68 offset:18464
	s_waitcnt lgkmcnt(10)
	v_mfma_f32_32x32x16_bf16 v[34:49], v[94:97], v[126:129], v[34:49]
	ds_read_b128 v[90:93], v1 offset:55328
	global_load_dwordx4 v[102:105], v[70:71], off offset:1408
	global_load_dwordx4 v[106:109], v[74:75], off offset:1408
	global_load_dwordx4 v[110:113], v[78:79], off offset:1408
	global_load_dwordx4 v[114:117], v[84:85], off offset:1408
	global_load_dwordx4 v[118:121], v[82:83], off offset:1408
	global_load_dwordx4 v[122:125], v[80:81], off offset:1408
	global_load_dwordx4 v[140:143], v[72:73], off offset:1408
	global_load_dwordx4 v[144:147], v[76:77], off offset:1408
	s_waitcnt lgkmcnt(10)
	v_mfma_f32_32x32x16_bf16 v[50:65], v[94:97], v[130:133], v[50:65]
	ds_read_b128 v[94:97], v1 offset:59936
	s_waitcnt lgkmcnt(1)
	v_mfma_f32_32x32x16_bf16 v[34:49], v[86:89], v[90:93], v[34:49]
	s_waitcnt lgkmcnt(0)
	v_mfma_f32_32x32x16_bf16 v[50:65], v[86:89], v[94:97], v[50:65]
	ds_read_b128 v[86:89], v68 offset:23072
	v_mfma_f32_32x32x16_bf16 v[2:17], v[98:101], v[126:129], v[2:17]
	v_mfma_f32_32x32x16_bf16 v[18:33], v[98:101], v[130:133], v[18:33]
	ds_read_b128 v[98:101], v68 offset:23136
	s_waitcnt lgkmcnt(1)
	v_mfma_f32_32x32x16_bf16 v[2:17], v[86:89], v[90:93], v[2:17]
	ds_read_b128 v[90:93], v1 offset:55360
	v_mfma_f32_32x32x16_bf16 v[18:33], v[86:89], v[94:97], v[18:33]
	ds_read_b128 v[86:89], v68 offset:18496
	ds_read_b128 v[94:97], v1 offset:59968
	s_waitcnt lgkmcnt(1)
	v_mfma_f32_32x32x16_bf16 v[34:49], v[86:89], v[90:93], v[34:49]
	s_waitcnt lgkmcnt(0)
	v_mfma_f32_32x32x16_bf16 v[50:65], v[86:89], v[94:97], v[50:65]
	ds_read_b128 v[86:89], v68 offset:23104
	s_waitcnt lgkmcnt(0)
	v_mfma_f32_32x32x16_bf16 v[2:17], v[86:89], v[90:93], v[2:17]
	ds_read_b128 v[90:93], v1 offset:55392
	v_mfma_f32_32x32x16_bf16 v[18:33], v[86:89], v[94:97], v[18:33]
	ds_read_b128 v[86:89], v68 offset:18528
	ds_read_b128 v[94:97], v1 offset:60000
	s_waitcnt lgkmcnt(1)
	v_mfma_f32_32x32x16_bf16 v[34:49], v[86:89], v[90:93], v[34:49]
	s_waitcnt lgkmcnt(0)
	v_mfma_f32_32x32x16_bf16 v[50:65], v[86:89], v[94:97], v[50:65]
	v_mfma_f32_32x32x16_bf16 v[2:17], v[98:101], v[90:93], v[2:17]
	v_mfma_f32_32x32x16_bf16 v[18:33], v[98:101], v[94:97], v[18:33]
	s_setprio 0
	s_barrier
	ds_read_b128 v[94:97], v68
	ds_read_b128 v[98:101], v68 offset:4608
	ds_read_b128 v[126:129], v1 offset:36864
	ds_read_b128 v[130:133], v1 offset:41472
	s_waitcnt vmcnt(1)
	ds_write_b128 v66, v[140:143] offset:18432
	ds_write_b128 v66, v[102:105] offset:23040
	ds_write_b128 v66, v[106:109] offset:27648
	ds_write_b128 v66, v[110:113] offset:32256
	s_waitcnt vmcnt(0)
	ds_write_b128 v66, v[144:147] offset:55296
	ds_write_b128 v66, v[122:125] offset:59904
	ds_write_b128 v66, v[118:121] offset:64512
	ds_write_b128 v69, v[114:117] offset:32256
	s_setprio 1
	ds_read_b128 v[86:89], v68 offset:32
	s_waitcnt lgkmcnt(10)
	v_mfma_f32_32x32x16_bf16 v[34:49], v[94:97], v[126:129], v[34:49]
	ds_read_b128 v[90:93], v1 offset:36896
	global_load_dwordx4 v[102:105], v[70:71], off offset:1536
	global_load_dwordx4 v[106:109], v[74:75], off offset:1536
	global_load_dwordx4 v[110:113], v[78:79], off offset:1536
	global_load_dwordx4 v[114:117], v[84:85], off offset:1536
	global_load_dwordx4 v[118:121], v[82:83], off offset:1536
	global_load_dwordx4 v[122:125], v[80:81], off offset:1536
	global_load_dwordx4 v[140:143], v[72:73], off offset:1536
	global_load_dwordx4 v[144:147], v[76:77], off offset:1536
	s_waitcnt lgkmcnt(10)
	v_mfma_f32_32x32x16_bf16 v[50:65], v[94:97], v[130:133], v[50:65]
	ds_read_b128 v[94:97], v1 offset:41504
	s_waitcnt lgkmcnt(1)
	v_mfma_f32_32x32x16_bf16 v[34:49], v[86:89], v[90:93], v[34:49]
	s_waitcnt lgkmcnt(0)
	v_mfma_f32_32x32x16_bf16 v[50:65], v[86:89], v[94:97], v[50:65]
	ds_read_b128 v[86:89], v68 offset:4640
	v_mfma_f32_32x32x16_bf16 v[2:17], v[98:101], v[126:129], v[2:17]
	v_mfma_f32_32x32x16_bf16 v[18:33], v[98:101], v[130:133], v[18:33]
	ds_read_b128 v[98:101], v68 offset:4704
	s_waitcnt lgkmcnt(1)
	v_mfma_f32_32x32x16_bf16 v[2:17], v[86:89], v[90:93], v[2:17]
	ds_read_b128 v[90:93], v1 offset:36928
	v_mfma_f32_32x32x16_bf16 v[18:33], v[86:89], v[94:97], v[18:33]
	ds_read_b128 v[86:89], v68 offset:64
	ds_read_b128 v[94:97], v1 offset:41536
	s_waitcnt lgkmcnt(1)
	v_mfma_f32_32x32x16_bf16 v[34:49], v[86:89], v[90:93], v[34:49]
	s_waitcnt lgkmcnt(0)
	v_mfma_f32_32x32x16_bf16 v[50:65], v[86:89], v[94:97], v[50:65]
	ds_read_b128 v[86:89], v68 offset:4672
	s_waitcnt lgkmcnt(0)
	v_mfma_f32_32x32x16_bf16 v[2:17], v[86:89], v[90:93], v[2:17]
	ds_read_b128 v[90:93], v1 offset:36960
	v_mfma_f32_32x32x16_bf16 v[18:33], v[86:89], v[94:97], v[18:33]
	ds_read_b128 v[86:89], v68 offset:96
	ds_read_b128 v[94:97], v1 offset:41568
	s_waitcnt lgkmcnt(1)
	v_mfma_f32_32x32x16_bf16 v[34:49], v[86:89], v[90:93], v[34:49]
	s_waitcnt lgkmcnt(0)
	v_mfma_f32_32x32x16_bf16 v[50:65], v[86:89], v[94:97], v[50:65]
	v_mfma_f32_32x32x16_bf16 v[2:17], v[98:101], v[90:93], v[2:17]
	v_mfma_f32_32x32x16_bf16 v[18:33], v[98:101], v[94:97], v[18:33]
	s_setprio 0
	s_barrier
; #define MFMA(a, b, c) __builtin_amdgcn_mfma_f32_32x32x16_bf16((a), (b), (c), 0, 0, 0)
; template <int TM, int TN>
; DI void gemm_mainloop(const u16* __restrict__ A, long lda, const u16* __restrict__ Bt, long ldb, int K, char* smem,
;                       f32x16 (&acc)[TM][TN]) {
;     ...
;   for (int kt = 0; kt < nk; kt++) {
;     const int buf = kt & 1;
;     const u16* cA = sA + buf * BM * LD + (wm * 32 * TM + r) * LD + h * 8;
;     const u16* cB = sB + buf * BN * LD + (wn * 32 * TN + r) * LD + h * 8;
;     bf16x8 af[TM], bfr[TN];
; #pragma unroll
;     for (int tm = 0; tm < TM; tm++) af[tm] = *(const bf16x8*)(cA + tm * 32 * LD);
; #pragma unroll
;     for (int tn = 0; tn < TN; tn++) bfr[tn] = *(const bf16x8*)(cB + tn * 32 * LD);
;     if (kt + 1 < nk) GEMM_SSTORE(buf ^ 1)
;     __builtin_amdgcn_sched_barrier(0);
;     __builtin_amdgcn_s_setprio(1);
; #pragma unroll
;     for (int tm = 0; tm < TM; tm++)
; #pragma unroll
;       for (int tn = 0; tn < TN; tn++) acc[tm][tn] = MFMA(af[tm], bfr[tn], acc[tm][tn]);
; #pragma unroll
;     for (int tm = 0; tm < TM; tm++) af[tm] = *(const bf16x8*)(cA + tm * 32 * LD + 16);
; #pragma unroll
;     for (int tn = 0; tn < TN; tn++) bfr[tn] = *(const bf16x8*)(cB + tn * 32 * LD + 16);
; #pragma unroll
;     for (int tm = 0; tm < TM; tm++)
; #pragma unroll
;       for (int tn = 0; tn < TN; tn++) acc[tm][tn] = MFMA(af[tm], bfr[tn], acc[tm][tn]);
;     __builtin_amdgcn_sched_group_barrier(0x8, 4, 0);
;     if (kt + 2 < nk) GEMM_GLOAD((kt + 2) * 64)
; #pragma unroll
;     for (int ks = 2; ks < 4; ks++) {
; #pragma unroll
;       for (int tm = 0; tm < TM; tm++) af[tm] = *(const bf16x8*)(cA + tm * 32 * LD + ks * 16);
; #pragma unroll
;       for (int tn = 0; tn < TN; tn++) bfr[tn] = *(const bf16x8*)(cB + tn * 32 * LD + ks * 16);
; #pragma unroll
;       for (int tm = 0; tm < TM; tm++)
; #pragma unroll
;         for (int tn = 0; tn < TN; tn++) acc[tm][tn] = MFMA(af[tm], bfr[tn], acc[tm][tn]);
;     }
	ds_read_b128 v[94:97], v68 offset:18432
	ds_read_b128 v[98:101], v68 offset:23040
	ds_read_b128 v[126:129], v1 offset:55296
	ds_read_b128 v[130:133], v1 offset:59904
	s_waitcnt vmcnt(1)
	ds_write_b128 v66, v[140:143]
	ds_write_b128 v66, v[102:105] offset:4608
	ds_write_b128 v66, v[106:109] offset:9216
	ds_write_b128 v66, v[110:113] offset:13824
	s_waitcnt vmcnt(0)
	ds_write_b128 v66, v[144:147] offset:36864
	ds_write_b128 v66, v[122:125] offset:41472
	ds_write_b128 v66, v[118:121] offset:46080
	ds_write_b128 v66, v[114:117] offset:50688
	s_setprio 1
	ds_read_b128 v[86:89], v68 offset:18464
	s_waitcnt lgkmcnt(10)
	v_mfma_f32_32x32x16_bf16 v[34:49], v[94:97], v[126:129], v[34:49]
	ds_read_b128 v[90:93], v1 offset:55328
	global_load_dwordx4 v[102:105], v[70:71], off offset:1664
	global_load_dwordx4 v[106:109], v[74:75], off offset:1664
	global_load_dwordx4 v[110:113], v[78:79], off offset:1664
	global_load_dwordx4 v[114:117], v[84:85], off offset:1664
	global_load_dwordx4 v[118:121], v[82:83], off offset:1664
	global_load_dwordx4 v[122:125], v[80:81], off offset:1664
	global_load_dwordx4 v[140:143], v[72:73], off offset:1664
	global_load_dwordx4 v[144:147], v[76:77], off offset:1664
	s_waitcnt lgkmcnt(10)
	v_mfma_f32_32x32x16_bf16 v[50:65], v[94:97], v[130:133], v[50:65]
	ds_read_b128 v[94:97], v1 offset:59936
	s_waitcnt lgkmcnt(1)
	v_mfma_f32_32x32x16_bf16 v[34:49], v[86:89], v[90:93], v[34:49]
	s_waitcnt lgkmcnt(0)
	v_mfma_f32_32x32x16_bf16 v[50:65], v[86:89], v[94:97], v[50:65]
	ds_read_b128 v[86:89], v68 offset:23072
	v_mfma_f32_32x32x16_bf16 v[2:17], v[98:101], v[126:129], v[2:17]
	v_mfma_f32_32x32x16_bf16 v[18:33], v[98:101], v[130:133], v[18:33]
	ds_read_b128 v[98:101], v68 offset:23136
	s_waitcnt lgkmcnt(1)
	v_mfma_f32_32x32x16_bf16 v[2:17], v[86:89], v[90:93], v[2:17]
	ds_read_b128 v[90:93], v1 offset:55360
	v_mfma_f32_32x32x16_bf16 v[18:33], v[86:89], v[94:97], v[18:33]
	ds_read_b128 v[86:89], v68 offset:18496
	ds_read_b128 v[94:97], v1 offset:59968
	s_waitcnt lgkmcnt(1)
	v_mfma_f32_32x32x16_bf16 v[34:49], v[86:89], v[90:93], v[34:49]
	s_waitcnt lgkmcnt(0)
	v_mfma_f32_32x32x16_bf16 v[50:65], v[86:89], v[94:97], v[50:65]
	ds_read_b128 v[86:89], v68 offset:23104
	s_waitcnt lgkmcnt(0)
	v_mfma_f32_32x32x16_bf16 v[2:17], v[86:89], v[90:93], v[2:17]
	ds_read_b128 v[90:93], v1 offset:55392
	v_mfma_f32_32x32x16_bf16 v[18:33], v[86:89], v[94:97], v[18:33]
	ds_read_b128 v[86:89], v68 offset:18528
	ds_read_b128 v[94:97], v1 offset:60000
	s_waitcnt lgkmcnt(1)
	v_mfma_f32_32x32x16_bf16 v[34:49], v[86:89], v[90:93], v[34:49]
	s_waitcnt lgkmcnt(0)
	v_mfma_f32_32x32x16_bf16 v[50:65], v[86:89], v[94:97], v[50:65]
	v_mfma_f32_32x32x16_bf16 v[2:17], v[98:101], v[90:93], v[2:17]
	v_mfma_f32_32x32x16_bf16 v[18:33], v[98:101], v[94:97], v[18:33]
	s_setprio 0
	s_barrier
	ds_read_b128 v[94:97], v68
	ds_read_b128 v[98:101], v68 offset:4608
	ds_read_b128 v[126:129], v1 offset:36864
	ds_read_b128 v[130:133], v1 offset:41472
	s_waitcnt vmcnt(1)
	ds_write_b128 v66, v[140:143] offset:18432
	ds_write_b128 v66, v[102:105] offset:23040
	ds_write_b128 v66, v[106:109] offset:27648
	ds_write_b128 v66, v[110:113] offset:32256
	s_waitcnt vmcnt(0)
	ds_write_b128 v66, v[144:147] offset:55296
	ds_write_b128 v66, v[122:125] offset:59904
	ds_write_b128 v66, v[118:121] offset:64512
	ds_write_b128 v69, v[114:117] offset:32256
	s_setprio 1
	ds_read_b128 v[86:89], v68 offset:32
	s_waitcnt lgkmcnt(10)
	v_mfma_f32_32x32x16_bf16 v[34:49], v[94:97], v[126:129], v[34:49]
	ds_read_b128 v[90:93], v1 offset:36896
	global_load_dwordx4 v[102:105], v[70:71], off offset:1792
	global_load_dwordx4 v[106:109], v[74:75], off offset:1792
	global_load_dwordx4 v[110:113], v[78:79], off offset:1792
	global_load_dwordx4 v[114:117], v[84:85], off offset:1792
	global_load_dwordx4 v[118:121], v[82:83], off offset:1792
	global_load_dwordx4 v[122:125], v[80:81], off offset:1792
	global_load_dwordx4 v[140:143], v[72:73], off offset:1792
	global_load_dwordx4 v[144:147], v[76:77], off offset:1792
	s_waitcnt lgkmcnt(10)
	v_mfma_f32_32x32x16_bf16 v[50:65], v[94:97], v[130:133], v[50:65]
	ds_read_b128 v[94:97], v1 offset:41504
	s_waitcnt lgkmcnt(1)
	v_mfma_f32_32x32x16_bf16 v[34:49], v[86:89], v[90:93], v[34:49]
	s_waitcnt lgkmcnt(0)
	v_mfma_f32_32x32x16_bf16 v[50:65], v[86:89], v[94:97], v[50:65]
	ds_read_b128 v[86:89], v68 offset:4640
	v_mfma_f32_32x32x16_bf16 v[2:17], v[98:101], v[126:129], v[2:17]
	v_mfma_f32_32x32x16_bf16 v[18:33], v[98:101], v[130:133], v[18:33]
	ds_read_b128 v[98:101], v68 offset:4704
	s_waitcnt lgkmcnt(1)
	v_mfma_f32_32x32x16_bf16 v[2:17], v[86:89], v[90:93], v[2:17]
	ds_read_b128 v[90:93], v1 offset:36928
	v_mfma_f32_32x32x16_bf16 v[18:33], v[86:89], v[94:97], v[18:33]
	ds_read_b128 v[86:89], v68 offset:64
	ds_read_b128 v[94:97], v1 offset:41536
	s_waitcnt lgkmcnt(1)
	v_mfma_f32_32x32x16_bf16 v[34:49], v[86:89], v[90:93], v[34:49]
	s_waitcnt lgkmcnt(0)
	v_mfma_f32_32x32x16_bf16 v[50:65], v[86:89], v[94:97], v[50:65]
	ds_read_b128 v[86:89], v68 offset:4672
	s_waitcnt lgkmcnt(0)
	v_mfma_f32_32x32x16_bf16 v[2:17], v[86:89], v[90:93], v[2:17]
	ds_read_b128 v[90:93], v1 offset:36960
	v_mfma_f32_32x32x16_bf16 v[18:33], v[86:89], v[94:97], v[18:33]
	ds_read_b128 v[86:89], v68 offset:96
	ds_read_b128 v[94:97], v1 offset:41568
	s_waitcnt lgkmcnt(1)
	v_mfma_f32_32x32x16_bf16 v[34:49], v[86:89], v[90:93], v[34:49]
	s_waitcnt lgkmcnt(0)
	v_mfma_f32_32x32x16_bf16 v[50:65], v[86:89], v[94:97], v[50:65]
	v_mfma_f32_32x32x16_bf16 v[2:17], v[98:101], v[90:93], v[2:17]
	v_mfma_f32_32x32x16_bf16 v[18:33], v[98:101], v[94:97], v[18:33]
	s_setprio 0
	s_barrier
; #define MFMA(a, b, c) __builtin_amdgcn_mfma_f32_32x32x16_bf16((a), (b), (c), 0, 0, 0)
; template <int TM, int TN>
; DI void gemm_mainloop(const u16* __restrict__ A, long lda, const u16* __restrict__ Bt, long ldb, int K, char* smem,
;                       f32x16 (&acc)[TM][TN]) {
;     ...
;   for (int kt = 0; kt < nk; kt++) {
;     const int buf = kt & 1;
;     const u16* cA = sA + buf * BM * LD + (wm * 32 * TM + r) * LD + h * 8;
;     const u16* cB = sB + buf * BN * LD + (wn * 32 * TN + r) * LD + h * 8;
;     bf16x8 af[TM], bfr[TN];
; #pragma unroll
;     for (int tm = 0; tm < TM; tm++) af[tm] = *(const bf16x8*)(cA + tm * 32 * LD);
; #pragma unroll
;     for (int tn = 0; tn < TN; tn++) bfr[tn] = *(const bf16x8*)(cB + tn * 32 * LD);
;     if (kt + 1 < nk) GEMM_SSTORE(buf ^ 1)
;     __builtin_amdgcn_sched_barrier(0);
;     __builtin_amdgcn_s_setprio(1);
; #pragma unroll
;     for (int tm = 0; tm < TM; tm++)
; #pragma unroll
;       for (int tn = 0; tn < TN; tn++) acc[tm][tn] = MFMA(af[tm], bfr[tn], acc[tm][tn]);
; #pragma unroll
;     for (int tm = 0; tm < TM; tm++) af[tm] = *(const bf16x8*)(cA + tm * 32 * LD + 16);
; #pragma unroll
;     for (int tn = 0; tn < TN; tn++) bfr[tn] = *(const bf16x8*)(cB + tn * 32 * LD + 16);
; #pragma unroll
;     for (int tm = 0; tm < TM; tm++)
; #pragma unroll
;       for (int tn = 0; tn < TN; tn++) acc[tm][tn] = MFMA(af[tm], bfr[tn], acc[tm][tn]);
;     __builtin_amdgcn_sched_group_barrier(0x8, 4, 0);
;     if (kt + 2 < nk) GEMM_GLOAD((kt + 2) * 64)
; #pragma unroll
;     for (int ks = 2; ks < 4; ks++) {
; #pragma unroll
;       for (int tm = 0; tm < TM; tm++) af[tm] = *(const bf16x8*)(cA + tm * 32 * LD + ks * 16);
; #pragma unroll
;       for (int tn = 0; tn < TN; tn++) bfr[tn] = *(const bf16x8*)(cB + tn * 32 * LD + ks * 16);
; #pragma unroll
;       for (int tm = 0; tm < TM; tm++)
; #pragma unroll
;         for (int tn = 0; tn < TN; tn++) acc[tm][tn] = MFMA(af[tm], bfr[tn], acc[tm][tn]);
;     }
	ds_read_b128 v[94:97], v68 offset:18432
	ds_read_b128 v[98:101], v68 offset:23040
	ds_read_b128 v[126:129], v1 offset:55296
	ds_read_b128 v[130:133], v1 offset:59904
	s_waitcnt vmcnt(1)
	ds_write_b128 v66, v[140:143]
	ds_write_b128 v66, v[102:105] offset:4608
	ds_write_b128 v66, v[106:109] offset:9216
	ds_write_b128 v66, v[110:113] offset:13824
	s_waitcnt vmcnt(0)
	ds_write_b128 v66, v[144:147] offset:36864
	ds_write_b128 v66, v[122:125] offset:41472
	ds_write_b128 v66, v[118:121] offset:46080
	ds_write_b128 v66, v[114:117] offset:50688
	s_setprio 1
	ds_read_b128 v[86:89], v68 offset:18464
	s_waitcnt lgkmcnt(10)
	v_mfma_f32_32x32x16_bf16 v[34:49], v[94:97], v[126:129], v[34:49]
	ds_read_b128 v[90:93], v1 offset:55328
	global_load_dwordx4 v[102:105], v[70:71], off offset:1920
	global_load_dwordx4 v[106:109], v[74:75], off offset:1920
	global_load_dwordx4 v[110:113], v[78:79], off offset:1920
	global_load_dwordx4 v[114:117], v[84:85], off offset:1920
	global_load_dwordx4 v[118:121], v[82:83], off offset:1920
	global_load_dwordx4 v[122:125], v[80:81], off offset:1920
	global_load_dwordx4 v[140:143], v[72:73], off offset:1920
	global_load_dwordx4 v[144:147], v[76:77], off offset:1920
	s_waitcnt lgkmcnt(10)
	v_mfma_f32_32x32x16_bf16 v[50:65], v[94:97], v[130:133], v[50:65]
	ds_read_b128 v[94:97], v1 offset:59936
	s_waitcnt lgkmcnt(1)
	v_mfma_f32_32x32x16_bf16 v[34:49], v[86:89], v[90:93], v[34:49]
	s_waitcnt lgkmcnt(0)
	v_mfma_f32_32x32x16_bf16 v[50:65], v[86:89], v[94:97], v[50:65]
	ds_read_b128 v[86:89], v68 offset:23072
	v_mfma_f32_32x32x16_bf16 v[2:17], v[98:101], v[126:129], v[2:17]
	v_mfma_f32_32x32x16_bf16 v[18:33], v[98:101], v[130:133], v[18:33]
	ds_read_b128 v[98:101], v68 offset:23136
	s_waitcnt lgkmcnt(1)
	v_mfma_f32_32x32x16_bf16 v[2:17], v[86:89], v[90:93], v[2:17]
	ds_read_b128 v[90:93], v1 offset:55360
	v_mfma_f32_32x32x16_bf16 v[18:33], v[86:89], v[94:97], v[18:33]
	ds_read_b128 v[86:89], v68 offset:18496
	ds_read_b128 v[94:97], v1 offset:59968
	s_waitcnt lgkmcnt(1)
	v_mfma_f32_32x32x16_bf16 v[34:49], v[86:89], v[90:93], v[34:49]
	s_waitcnt lgkmcnt(0)
	v_mfma_f32_32x32x16_bf16 v[50:65], v[86:89], v[94:97], v[50:65]
	ds_read_b128 v[86:89], v68 offset:23104
	s_waitcnt lgkmcnt(0)
	v_mfma_f32_32x32x16_bf16 v[2:17], v[86:89], v[90:93], v[2:17]
	ds_read_b128 v[90:93], v1 offset:55392
	v_mfma_f32_32x32x16_bf16 v[18:33], v[86:89], v[94:97], v[18:33]
	ds_read_b128 v[86:89], v68 offset:18528
	ds_read_b128 v[94:97], v1 offset:60000
	s_waitcnt lgkmcnt(1)
	v_mfma_f32_32x32x16_bf16 v[34:49], v[86:89], v[90:93], v[34:49]
	s_waitcnt lgkmcnt(0)
	v_mfma_f32_32x32x16_bf16 v[50:65], v[86:89], v[94:97], v[50:65]
	s_nop 0
	v_mfma_f32_32x32x16_bf16 v[2:17], v[98:101], v[90:93], v[2:17]
	v_mfma_f32_32x32x16_bf16 v[18:33], v[98:101], v[94:97], v[18:33]
	s_setprio 0
	s_barrier
	ds_read_b128 v[74:77], v68
	ds_read_b128 v[78:81], v68 offset:4608
	ds_read_b128 v[82:85], v1 offset:36864
	ds_read_b128 v[90:93], v1 offset:41472
	s_waitcnt vmcnt(1)
	ds_write_b128 v66, v[140:143] offset:18432
	ds_write_b128 v66, v[102:105] offset:23040
	ds_write_b128 v66, v[106:109] offset:27648
	ds_write_b128 v66, v[110:113] offset:32256
	s_waitcnt vmcnt(0)
	ds_write_b128 v66, v[144:147] offset:55296
	ds_write_b128 v66, v[122:125] offset:59904
	ds_write_b128 v66, v[118:121] offset:64512
	ds_write_b128 v69, v[114:117] offset:32256
	s_setprio 1
	ds_read_b128 v[70:73], v68 offset:32
	s_waitcnt lgkmcnt(10)
	v_mfma_f32_32x32x16_bf16 v[34:49], v[74:77], v[82:85], v[34:49]
	s_waitcnt lgkmcnt(9)
	v_mfma_f32_32x32x16_bf16 v[50:65], v[74:77], v[90:93], v[50:65]
	ds_read_b128 v[74:77], v1 offset:36896
	v_mfma_f32_32x32x16_bf16 v[2:17], v[78:81], v[82:85], v[2:17]
	v_mfma_f32_32x32x16_bf16 v[18:33], v[78:81], v[90:93], v[18:33]
	ds_read_b128 v[78:81], v1 offset:41504
	s_waitcnt lgkmcnt(1)
	v_mfma_f32_32x32x16_bf16 v[34:49], v[70:73], v[74:77], v[34:49]
	s_waitcnt lgkmcnt(0)
	v_mfma_f32_32x32x16_bf16 v[50:65], v[70:73], v[78:81], v[50:65]
	ds_read_b128 v[70:73], v68 offset:4640
	s_waitcnt lgkmcnt(0)
	v_mfma_f32_32x32x16_bf16 v[2:17], v[70:73], v[74:77], v[2:17]
	ds_read_b128 v[74:77], v1 offset:36928
	v_mfma_f32_32x32x16_bf16 v[18:33], v[70:73], v[78:81], v[18:33]
	ds_read_b128 v[70:73], v68 offset:64
	ds_read_b128 v[78:81], v1 offset:41536
	s_waitcnt lgkmcnt(1)
	v_mfma_f32_32x32x16_bf16 v[34:49], v[70:73], v[74:77], v[34:49]
	s_waitcnt lgkmcnt(0)
	v_mfma_f32_32x32x16_bf16 v[50:65], v[70:73], v[78:81], v[50:65]
	ds_read_b128 v[70:73], v68 offset:4672
	s_waitcnt lgkmcnt(0)
	v_mfma_f32_32x32x16_bf16 v[2:17], v[70:73], v[74:77], v[2:17]
	ds_read_b128 v[74:77], v1 offset:36960
	v_mfma_f32_32x32x16_bf16 v[18:33], v[70:73], v[78:81], v[18:33]
	ds_read_b128 v[70:73], v68 offset:96
	ds_read_b128 v[78:81], v1 offset:41568
	s_waitcnt lgkmcnt(1)
	v_mfma_f32_32x32x16_bf16 v[34:49], v[70:73], v[74:77], v[34:49]
	s_waitcnt lgkmcnt(0)
	v_mfma_f32_32x32x16_bf16 v[50:65], v[70:73], v[78:81], v[50:65]
	ds_read_b128 v[70:73], v68 offset:4704
	s_waitcnt lgkmcnt(0)
	v_mfma_f32_32x32x16_bf16 v[2:17], v[70:73], v[74:77], v[2:17]
	v_mfma_f32_32x32x16_bf16 v[18:33], v[70:73], v[78:81], v[18:33]
	s_setprio 0
	s_barrier
; #define MFMA(a, b, c) __builtin_amdgcn_mfma_f32_32x32x16_bf16((a), (b), (c), 0, 0, 0)
; DI int crow(int i, int h) { return (i & 3) + 8 * (i >> 2) + 4 * h; }
; template <int TM, int TN>
; DI void gemm_mainloop(const u16* __restrict__ A, long lda, const u16* __restrict__ Bt, long ldb, int K, char* smem,
;                       f32x16 (&acc)[TM][TN]) {
;     ...
;     for (int tm = 0; tm < TM; tm++) af[tm] = *(const bf16x8*)(cA + tm * 32 * LD + 16);
; #pragma unroll
;     for (int tn = 0; tn < TN; tn++) bfr[tn] = *(const bf16x8*)(cB + tn * 32 * LD + 16);
; #pragma unroll
;     for (int tm = 0; tm < TM; tm++)
; #pragma unroll
;       for (int tn = 0; tn < TN; tn++) acc[tm][tn] = MFMA(af[tm], bfr[tn], acc[tm][tn]);
;     __builtin_amdgcn_sched_group_barrier(0x8, 4, 0);
;     if (kt + 2 < nk) GEMM_GLOAD((kt + 2) * 64)
; #pragma unroll
;     for (int ks = 2; ks < 4; ks++) {
; #pragma unroll
;       for (int tm = 0; tm < TM; tm++) af[tm] = *(const bf16x8*)(cA + tm * 32 * LD + ks * 16);
; #pragma unroll
;       for (int tn = 0; tn < TN; tn++) bfr[tn] = *(const bf16x8*)(cB + tn * 32 * LD + ks * 16);
; #pragma unroll
;       for (int tm = 0; tm < TM; tm++)
; #pragma unroll
;         for (int tn = 0; tn < TN; tn++) acc[tm][tn] = MFMA(af[tm], bfr[tn], acc[tm][tn]);
;     }
; template <int TM, int TN, class Epi>
; DI void gemm_tile(const u16* A, long lda, const u16* Bt, long ldb, int K, int m0, int n0, char* smem, const Epi& epi) {
;     ...
; #pragma unroll
;   for (int tm = 0; tm < TM; tm++)
; #pragma unroll
;     for (int tn = 0; tn < TN; tn++)
; #pragma unroll
;       for (int i = 0; i < 16; i++)
;         Ct[(wm * 32 * TM + tm * 32 + crow(i, h)) * LDC + wn * 32 * TN + tn * 32 + r] = acc[tm][tn][i];
;   __syncthreads();
	ds_read_b128 v[70:73], v68 offset:18432
	ds_read_b128 v[74:77], v68 offset:23040
	ds_read_b128 v[78:81], v1 offset:55296
	ds_read_b128 v[82:85], v1 offset:59904
	s_setprio 1
	s_waitcnt lgkmcnt(1)
	v_mfma_f32_32x32x16_bf16 v[34:49], v[70:73], v[78:81], v[34:49]
	s_waitcnt lgkmcnt(0)
	v_mfma_f32_32x32x16_bf16 v[50:65], v[70:73], v[82:85], v[50:65]
	ds_read_b128 v[70:73], v68 offset:18464
	v_mfma_f32_32x32x16_bf16 v[2:17], v[74:77], v[78:81], v[2:17]
	ds_read_b128 v[78:81], v1 offset:59936
	v_mfma_f32_32x32x16_bf16 v[18:33], v[74:77], v[82:85], v[18:33]
	ds_read_b128 v[74:77], v1 offset:55328
	s_waitcnt lgkmcnt(0)
	v_mfma_f32_32x32x16_bf16 v[34:49], v[70:73], v[74:77], v[34:49]
	v_mfma_f32_32x32x16_bf16 v[50:65], v[70:73], v[78:81], v[50:65]
	ds_read_b128 v[70:73], v68 offset:23072
	s_waitcnt lgkmcnt(0)
	v_mfma_f32_32x32x16_bf16 v[2:17], v[70:73], v[74:77], v[2:17]
	ds_read_b128 v[74:77], v1 offset:55360
	v_mfma_f32_32x32x16_bf16 v[18:33], v[70:73], v[78:81], v[18:33]
	ds_read_b128 v[70:73], v68 offset:18496
	ds_read_b128 v[78:81], v1 offset:59968
	s_waitcnt lgkmcnt(1)
	v_mfma_f32_32x32x16_bf16 v[34:49], v[70:73], v[74:77], v[34:49]
	s_waitcnt lgkmcnt(0)
	v_mfma_f32_32x32x16_bf16 v[50:65], v[70:73], v[78:81], v[50:65]
	ds_read_b128 v[70:73], v68 offset:23104
	s_waitcnt lgkmcnt(0)
	v_mfma_f32_32x32x16_bf16 v[2:17], v[70:73], v[74:77], v[2:17]
	ds_read_b128 v[74:77], v1 offset:55392
	v_mfma_f32_32x32x16_bf16 v[18:33], v[70:73], v[78:81], v[18:33]
	ds_read_b128 v[70:73], v68 offset:18528
	ds_read_b128 v[78:81], v1 offset:60000
	s_waitcnt lgkmcnt(1)
	v_mfma_f32_32x32x16_bf16 v[34:49], v[70:73], v[74:77], v[34:49]
	s_waitcnt lgkmcnt(0)
	v_mfma_f32_32x32x16_bf16 v[50:65], v[70:73], v[78:81], v[50:65]
	ds_read_b128 v[68:71], v68 offset:23136
	s_waitcnt lgkmcnt(0)
	v_mfma_f32_32x32x16_bf16 v[2:17], v[68:71], v[74:77], v[2:17]
	v_mfma_f32_32x32x16_bf16 v[18:33], v[68:71], v[78:81], v[18:33]
	s_setprio 0
	v_mov_b32_e32 v1, v0
	s_barrier
	s_lshl_b64 s[6:7], s[6:7], 1
	v_lshrrev_b32_e32 v66, 1, v1
	v_and_b32_e32 v66, 0xfffffc0, v66
	v_lshrrev_b32_e32 v68, 3, v1
	v_and_or_b32 v66, v68, 4, v66
	v_and_b32_e32 v68, 0x5f, v1
	v_mul_lo_u32 v66, v66, s20
	v_lshl_add_u32 v66, v68, 2, v66
	ds_write2_b32 v66, v34, v50 offset1:32
	v_add_u32_e32 v34, 0x400, v66
	ds_write2_b32 v34, v36, v52 offset0:8 offset1:40
	ds_write2_b32 v34, v37, v53 offset0:140 offset1:172
	v_add_u32_e32 v34, 0x1000, v66
	ds_write2_b32 v34, v38, v54 offset0:32 offset1:64
	ds_write2_b32 v34, v39, v55 offset0:164 offset1:196
	v_add_u32_e32 v34, 0x1400, v66
	ds_write2_b32 v34, v40, v56 offset0:40 offset1:72
	ds_write2_b32 v34, v41, v57 offset0:172 offset1:204
	v_add_u32_e32 v34, 0x2000, v66
	ds_write2_b32 v34, v42, v58 offset0:64 offset1:96
	ds_write2_b32 v34, v43, v59 offset0:196 offset1:228
	v_add_u32_e32 v34, 0x2400, v66
	ds_write2_b32 v34, v44, v60 offset0:72 offset1:104
	ds_write2_b32 v34, v45, v61 offset0:204 offset1:236
	v_add_u32_e32 v34, 0x3000, v66
	ds_write2_b32 v34, v46, v62 offset0:96 offset1:128
	v_add_u32_e32 v34, 0x3200, v66
	ds_write2_b32 v34, v47, v63 offset0:100 offset1:132
	v_add_u32_e32 v34, 0x3400, v66
	ds_write2_b32 v34, v48, v64 offset0:104 offset1:136
	v_add_u32_e32 v34, 0x3600, v66
	ds_write2_b32 v34, v49, v65 offset0:108 offset1:140
	v_add_u32_e32 v34, 0x4000, v66
	ds_write2_b32 v34, v2, v18 offset0:128 offset1:160
	v_add_u32_e32 v2, 0x4400, v66
	ds_write2_b32 v2, v3, v19 offset0:4 offset1:36
	ds_write2_b32 v2, v4, v20 offset0:136 offset1:168
	v_add_u32_e32 v2, 0x4800, v66
	ds_write2_b32 v2, v5, v21 offset0:12 offset1:44
	v_add_u32_e32 v2, 0x5000, v66
	ds_write2_b32 v2, v6, v22 offset0:160 offset1:192
	v_add_u32_e32 v2, 0x5400, v66
	ds_write2_b32 v2, v7, v23 offset0:36 offset1:68
	ds_write2_b32 v2, v8, v24 offset0:168 offset1:200
	v_add_u32_e32 v2, 0x5800, v66
	ds_write2_b32 v2, v9, v25 offset0:44 offset1:76
	v_add_u32_e32 v2, 0x6000, v66
	ds_write2_b32 v2, v10, v26 offset0:192 offset1:224
	v_add_u32_e32 v2, 0x6400, v66
	ds_write2_b32 v2, v11, v27 offset0:68 offset1:100
	ds_write2_b32 v2, v12, v28 offset0:200 offset1:232
	v_add_u32_e32 v2, 0x6800, v66
	ds_write2_b32 v2, v13, v29 offset0:76 offset1:108
	v_add_u32_e32 v2, 0x7200, v66
	ds_write2_b32 v2, v14, v30 offset0:96 offset1:128
	v_add_u32_e32 v2, 0x7400, v66
	ds_write2_b32 v2, v15, v31 offset0:100 offset1:132
	v_add_u32_e32 v2, 0x7600, v66
	ds_write2_b32 v2, v16, v32 offset0:104 offset1:136
	v_add_u32_e32 v2, 0x7800, v66
	ds_write2_b32 v2, v17, v33 offset0:108 offset1:140
	v_lshlrev_b32_e32 v2, 3, v1
	v_and_b32_e32 v3, 0x78, v2
	s_add_u32 s6, s3, s6
	ds_write2_b32 v66, v35, v51 offset0:132 offset1:164
	s_addc_u32 s7, s10, s7
	v_lshlrev_b32_e32 v66, 1, v3
	v_lshlrev_b32_e32 v2, 2, v3
	v_lshl_add_u64 v[4:5], s[6:7], 0, v[66:67]
	s_mov_b32 s6, 0
	s_waitcnt lgkmcnt(0)
	s_barrier
